# cache-policy lever: nt (streaming) hint on the one-shot weight-conversion / pool-prep global loads and stores of phase 0
# speedup vs baseline: 1.0013x; 1.0013x over previous
; #define LAS __attribute__((address_space(3)))
; __device__ __forceinline__ void transpose_item(const float* W, int ldn, int k0, int n0, const float* gk, bf16_t* WT, int ldk, int drow0, LAS float* scr, int lane, const float* gn = nullptr) {
;     const float gnv = gn ? gn[lane & 31] : 1.f;
;     float wv[32];
; #pragma unroll
;     for (int i = 0; i < 32; ++i) wv[i] = W[(size_t)(k0 + 2 * i + (lane >> 5)) * ldn + n0 + (lane & 31)];
; __device__ __forceinline__ void convert_weights(const Params& p, LAS unsigned char* lds, int gw, int NGW, int wave, int lane) {
;     ...
;         if (r < I_POOL) {
;             const int jg = r / 32, q = r % 32, kb = q / 8, nb = q % 8;
;             transpose_item(p.pool_w + (size_t)jg * 65536, 256, 64 * kb, 32 * nb, nullptr, (bf16_t*)(p.ws + WS_POOLW) + (size_t)(jg >> 2) * 1024 * 256, 256, (jg & 3) * 256 + 32 * nb, scr, lane, p.pool_scale + (size_t)(jg >> 2) * D + (jg & 3) * 256 + 32 * nb);
.LBB0_10:
	s_sext_i32_i8 s16, s7
	s_ashr_i32 s7, s6, 31
	s_lshl_b64 s[6:7], s[6:7], 18
	s_add_u32 s17, s86, s6
	v_readlane_b32 s24, v251, 1
	s_addc_u32 s7, s87, s7
	s_lshl_b32 s6, s16, 6
	s_lshl_b64 s[14:15], s[14:15], 19
	v_readlane_b32 s26, v251, 3
	v_readlane_b32 s27, v251, 4
	s_add_u32 s14, s26, s14
	s_addc_u32 s15, s27, s15
	s_add_i32 s0, s12, s0
	v_or_b32_e32 v6, s6, v1
	s_lshl_b64 s[12:13], s[12:13], 2
	s_add_u32 s12, s17, s12
	v_or_b32_e32 v12, 2, v6
	v_or_b32_e32 v14, 4, v6
	v_or_b32_e32 v16, 6, v6
	v_or_b32_e32 v22, 12, v6
	s_addc_u32 s13, s7, s13
	v_ashrrev_i32_e32 v7, 31, v6
	v_ashrrev_i32_e32 v13, 31, v12
	v_ashrrev_i32_e32 v15, 31, v14
	v_ashrrev_i32_e32 v17, 31, v16
	v_or_b32_e32 v18, 8, v6
	v_or_b32_e32 v20, 10, v6
	v_ashrrev_i32_e32 v23, 31, v22
	v_or_b32_e32 v52, 14, v6
	v_lshl_add_u64 v[8:9], s[12:13], 0, v[2:3]
	v_lshlrev_b64 v[10:11], 10, v[6:7]
	v_lshlrev_b64 v[12:13], 10, v[12:13]
	v_lshlrev_b64 v[14:15], 10, v[14:15]
	v_lshlrev_b64 v[16:17], 10, v[16:17]
	v_ashrrev_i32_e32 v19, 31, v18
	v_ashrrev_i32_e32 v21, 31, v20
	v_lshlrev_b64 v[22:23], 10, v[22:23]
	v_ashrrev_i32_e32 v53, 31, v52
	v_lshl_add_u64 v[10:11], v[8:9], 0, v[10:11]
	v_lshl_add_u64 v[12:13], v[8:9], 0, v[12:13]
	v_lshl_add_u64 v[14:15], v[8:9], 0, v[14:15]
	v_lshl_add_u64 v[16:17], v[8:9], 0, v[16:17]
	v_lshlrev_b64 v[18:19], 10, v[18:19]
	v_lshlrev_b64 v[20:21], 10, v[20:21]
	v_lshl_add_u64 v[22:23], v[8:9], 0, v[22:23]
	v_lshlrev_b64 v[52:53], 10, v[52:53]
	v_lshl_add_u64 v[18:19], v[8:9], 0, v[18:19]
	v_lshl_add_u64 v[20:21], v[8:9], 0, v[20:21]
	v_lshl_add_u64 v[52:53], v[8:9], 0, v[52:53]
	global_load_dword v51, v[10:11], off
	global_load_dword v54, v[12:13], off
	global_load_dword v55, v[14:15], off
	global_load_dword v56, v[16:17], off
	global_load_dword v57, v[18:19], off
	global_load_dword v58, v[20:21], off
	global_load_dword v59, v[22:23], off
	global_load_dword v60, v[52:53], off
	v_or_b32_e32 v10, 16, v6
	v_or_b32_e32 v12, 18, v6
	v_or_b32_e32 v14, 20, v6
	v_or_b32_e32 v16, 22, v6
	v_or_b32_e32 v22, 28, v6
	v_ashrrev_i32_e32 v11, 31, v10
	v_ashrrev_i32_e32 v13, 31, v12
	v_ashrrev_i32_e32 v15, 31, v14
	v_ashrrev_i32_e32 v17, 31, v16
	v_or_b32_e32 v18, 24, v6
	v_or_b32_e32 v20, 26, v6
	v_ashrrev_i32_e32 v23, 31, v22
	v_or_b32_e32 v52, 30, v6
	v_lshlrev_b64 v[10:11], 10, v[10:11]
	v_lshlrev_b64 v[12:13], 10, v[12:13]
	v_lshlrev_b64 v[14:15], 10, v[14:15]
	v_lshlrev_b64 v[16:17], 10, v[16:17]
	v_ashrrev_i32_e32 v19, 31, v18
	v_ashrrev_i32_e32 v21, 31, v20
	v_lshlrev_b64 v[22:23], 10, v[22:23]
	v_ashrrev_i32_e32 v53, 31, v52
	v_lshl_add_u64 v[10:11], v[8:9], 0, v[10:11]
	v_lshl_add_u64 v[12:13], v[8:9], 0, v[12:13]
	v_lshl_add_u64 v[14:15], v[8:9], 0, v[14:15]
	v_lshl_add_u64 v[16:17], v[8:9], 0, v[16:17]
	v_lshlrev_b64 v[18:19], 10, v[18:19]
	v_lshlrev_b64 v[20:21], 10, v[20:21]
	v_lshl_add_u64 v[22:23], v[8:9], 0, v[22:23]
	v_lshlrev_b64 v[52:53], 10, v[52:53]
	v_lshl_add_u64 v[18:19], v[8:9], 0, v[18:19]
	v_lshl_add_u64 v[20:21], v[8:9], 0, v[20:21]
	v_lshl_add_u64 v[52:53], v[8:9], 0, v[52:53]
	global_load_dword v61, v[10:11], off
	global_load_dword v62, v[12:13], off
	global_load_dword v63, v[14:15], off
	global_load_dword v64, v[16:17], off
	global_load_dword v65, v[18:19], off
	global_load_dword v66, v[20:21], off
	global_load_dword v67, v[22:23], off
	global_load_dword v68, v[52:53], off
	v_or_b32_e32 v10, 32, v6
	v_or_b32_e32 v12, 34, v6
	v_or_b32_e32 v14, 36, v6
	v_or_b32_e32 v16, 38, v6
	v_or_b32_e32 v22, 44, v6
	v_ashrrev_i32_e32 v11, 31, v10
	v_ashrrev_i32_e32 v13, 31, v12
	v_ashrrev_i32_e32 v15, 31, v14
	v_ashrrev_i32_e32 v17, 31, v16
	v_or_b32_e32 v18, 40, v6
	v_or_b32_e32 v20, 42, v6
	v_ashrrev_i32_e32 v23, 31, v22
	v_or_b32_e32 v52, 46, v6
	v_lshlrev_b64 v[10:11], 10, v[10:11]
	v_lshlrev_b64 v[12:13], 10, v[12:13]
	v_lshlrev_b64 v[14:15], 10, v[14:15]
	v_lshlrev_b64 v[16:17], 10, v[16:17]
	v_ashrrev_i32_e32 v19, 31, v18
	v_ashrrev_i32_e32 v21, 31, v20
	v_lshlrev_b64 v[22:23], 10, v[22:23]
	v_ashrrev_i32_e32 v53, 31, v52
	v_lshl_add_u64 v[10:11], v[8:9], 0, v[10:11]
	v_lshl_add_u64 v[12:13], v[8:9], 0, v[12:13]
	v_lshl_add_u64 v[14:15], v[8:9], 0, v[14:15]
	v_lshl_add_u64 v[16:17], v[8:9], 0, v[16:17]
	v_lshlrev_b64 v[18:19], 10, v[18:19]
	v_lshlrev_b64 v[20:21], 10, v[20:21]
	v_lshl_add_u64 v[22:23], v[8:9], 0, v[22:23]
	v_lshlrev_b64 v[52:53], 10, v[52:53]
	v_lshl_add_u64 v[18:19], v[8:9], 0, v[18:19]
	v_lshl_add_u64 v[20:21], v[8:9], 0, v[20:21]
	v_lshl_add_u64 v[52:53], v[8:9], 0, v[52:53]
	global_load_dword v69, v[10:11], off
	global_load_dword v70, v[12:13], off
	global_load_dword v71, v[14:15], off
	global_load_dword v72, v[16:17], off
	global_load_dword v73, v[18:19], off
	global_load_dword v74, v[20:21], off
	s_nop 0
	global_load_dword v22, v[22:23], off
	s_nop 0
	global_load_dword v23, v[52:53], off
	v_or_b32_e32 v10, 48, v6
	v_or_b32_e32 v12, 50, v6
	v_or_b32_e32 v14, 52, v6
	v_or_b32_e32 v16, 54, v6
	v_ashrrev_i32_e32 v11, 31, v10
	v_ashrrev_i32_e32 v13, 31, v12
	v_ashrrev_i32_e32 v15, 31, v14
	v_ashrrev_i32_e32 v17, 31, v16
	v_or_b32_e32 v18, 56, v6
	v_or_b32_e32 v20, 58, v6
	v_lshlrev_b64 v[10:11], 10, v[10:11]
	v_lshlrev_b64 v[12:13], 10, v[12:13]
	v_lshlrev_b64 v[14:15], 10, v[14:15]
	v_lshlrev_b64 v[16:17], 10, v[16:17]
	v_ashrrev_i32_e32 v19, 31, v18
	v_ashrrev_i32_e32 v21, 31, v20
	v_lshl_add_u64 v[10:11], v[8:9], 0, v[10:11]
	v_lshl_add_u64 v[12:13], v[8:9], 0, v[12:13]
	v_lshl_add_u64 v[14:15], v[8:9], 0, v[14:15]
	v_lshl_add_u64 v[16:17], v[8:9], 0, v[16:17]
	v_lshlrev_b64 v[18:19], 10, v[18:19]
	v_lshlrev_b64 v[20:21], 10, v[20:21]
	v_lshl_add_u64 v[18:19], v[8:9], 0, v[18:19]
	v_lshl_add_u64 v[20:21], v[8:9], 0, v[20:21]
	global_load_dword v52, v[10:11], off
	s_nop 0
	global_load_dword v12, v[12:13], off
	s_nop 0
	global_load_dword v13, v[14:15], off
	s_nop 0
	global_load_dword v14, v[16:17], off
	global_load_dword v15, v[18:19], off
	s_nop 0
	global_load_dword v16, v[20:21], off
	v_or_b32_e32 v10, 60, v6
	v_or_b32_e32 v6, 62, v6
	v_ashrrev_i32_e32 v11, 31, v10
	v_ashrrev_i32_e32 v7, 31, v6
	v_lshlrev_b64 v[10:11], 10, v[10:11]
	v_lshlrev_b64 v[6:7], 10, v[6:7]
	v_lshl_add_u64 v[10:11], v[8:9], 0, v[10:11]
	v_lshl_add_u64 v[6:7], v[8:9], 0, v[6:7]
	global_load_dword v8, v[10:11], off
	s_nop 0
	global_load_dword v6, v[6:7], off
	s_waitcnt vmcnt(31)
; #define LAS __attribute__((address_space(3)))
; __device__ __forceinline__ unsigned cvt_pk_bf16(float lo, float hi) { const f32x2 v = {lo, hi}; const bf16x2_t b = __builtin_convertvector(v, bf16x2_t); return __builtin_bit_cast(unsigned, b); }
; __device__ __forceinline__ void transpose_item(const float* W, int ldn, int k0, int n0, const float* gk, bf16_t* WT, int ldk, int drow0, LAS float* scr, int lane, const float* gn = nullptr) {
;     ...
;     for (int i = 0; i < 32; ++i) { const int kk = 2 * i + (lane >> 5); float v = wv[i] * gnv; if (gk) v *= gk[k0 + kk]; scr[kk * 33 + (lane & 31)] = v; }
;     asm volatile("s_waitcnt lgkmcnt(0)" ::: "memory");
;     const int c = lane & 7;
; #pragma unroll
;     for (int j = 0; j < 4; ++j) { const int n = (lane >> 3) + 8 * j; const LAS float* s = scr + (8 * c) * 33 + n;
;         u32x4 o; o.x = cvt_pk_bf16(s[0 * 33], s[1 * 33]); o.y = cvt_pk_bf16(s[2 * 33], s[3 * 33]); o.z = cvt_pk_bf16(s[4 * 33], s[5 * 33]); o.w = cvt_pk_bf16(s[6 * 33], s[7 * 33]);
;         *(u32x4*)(WT + (size_t)(drow0 + n) * ldk + k0 + 8 * c) = o; }
;     asm volatile("s_waitcnt lgkmcnt(0)" ::: "memory");
	v_mul_f32_e32 v7, v5, v51
	s_waitcnt vmcnt(30)
	v_mul_f32_e32 v9, v5, v54
	ds_write2_b32 v25, v7, v9 offset1:66
	s_waitcnt vmcnt(29)
	v_mul_f32_e32 v7, v5, v55
	s_waitcnt vmcnt(28)
	v_mul_f32_e32 v9, v5, v56
	ds_write2_b32 v25, v7, v9 offset0:132 offset1:198
	s_waitcnt vmcnt(27)
	v_mul_f32_e32 v7, v5, v57
	s_waitcnt vmcnt(26)
	v_mul_f32_e32 v9, v5, v58
	ds_write2_b32 v38, v7, v9 offset0:8 offset1:74
	s_waitcnt vmcnt(25)
	v_mul_f32_e32 v7, v5, v59
	s_waitcnt vmcnt(24)
	v_mul_f32_e32 v9, v5, v60
	ds_write2_b32 v38, v7, v9 offset0:140 offset1:206
	s_waitcnt vmcnt(23)
	v_mul_f32_e32 v7, v5, v61
	s_waitcnt vmcnt(22)
	v_mul_f32_e32 v9, v5, v62
	ds_write2_b32 v39, v7, v9 offset0:16 offset1:82
	s_waitcnt vmcnt(21)
	v_mul_f32_e32 v7, v5, v63
	s_waitcnt vmcnt(20)
	v_mul_f32_e32 v9, v5, v64
	ds_write2_b32 v39, v7, v9 offset0:148 offset1:214
	s_waitcnt vmcnt(19)
	v_mul_f32_e32 v7, v5, v65
	s_waitcnt vmcnt(18)
	v_mul_f32_e32 v9, v5, v66
	ds_write2_b32 v40, v7, v9 offset0:24 offset1:90
	s_waitcnt vmcnt(17)
	v_mul_f32_e32 v7, v5, v67
	s_waitcnt vmcnt(16)
	v_mul_f32_e32 v9, v5, v68
	ds_write2_b32 v40, v7, v9 offset0:156 offset1:222
	s_ashr_i32 s7, s6, 31
	s_lshl_b64 s[6:7], s[6:7], 1
	s_add_u32 s6, s14, s6
	v_or_b32_e32 v56, s0, v26
	s_addc_u32 s7, s15, s7
	v_ashrrev_i32_e32 v57, 31, v56
	v_lshlrev_b64 v[56:57], 9, v[56:57]
	v_readlane_b32 s25, v251, 2
	s_waitcnt vmcnt(15)
	v_mul_f32_e32 v7, v5, v69
	s_waitcnt vmcnt(14)
	v_mul_f32_e32 v9, v5, v70
	ds_write2_b32 v41, v7, v9 offset0:32 offset1:98
	s_waitcnt vmcnt(13)
	v_mul_f32_e32 v7, v5, v71
	s_waitcnt vmcnt(12)
	v_mul_f32_e32 v9, v5, v72
	ds_write2_b32 v41, v7, v9 offset0:164 offset1:230
	s_waitcnt vmcnt(11)
	v_mul_f32_e32 v7, v5, v73
	s_waitcnt vmcnt(10)
	v_mul_f32_e32 v9, v5, v74
	ds_write2_b32 v42, v7, v9 offset0:40 offset1:106
	s_waitcnt vmcnt(9)
	v_mul_f32_e32 v7, v5, v22
	s_waitcnt vmcnt(8)
	v_mul_f32_e32 v9, v5, v23
	ds_write2_b32 v42, v7, v9 offset0:172 offset1:238
	s_waitcnt vmcnt(7)
	v_mul_f32_e32 v7, v5, v52
	s_waitcnt vmcnt(6)
	v_mul_f32_e32 v9, v5, v12
	ds_write2_b32 v43, v7, v9 offset0:48 offset1:114
	s_waitcnt vmcnt(5)
	v_mul_f32_e32 v7, v5, v13
	s_waitcnt vmcnt(4)
	v_mul_f32_e32 v9, v5, v14
	ds_write2_b32 v43, v7, v9 offset0:180 offset1:246
	s_waitcnt vmcnt(3)
	v_mul_f32_e32 v7, v5, v15
	s_waitcnt vmcnt(2)
	v_mul_f32_e32 v9, v5, v16
	ds_write2_b32 v44, v7, v9 offset0:56 offset1:122
	s_waitcnt vmcnt(1)
	v_mul_f32_e32 v7, v5, v8
	s_waitcnt vmcnt(0)
	v_mul_f32_e32 v5, v5, v6
	ds_write2_b32 v44, v7, v5 offset0:188 offset1:254
	s_waitcnt lgkmcnt(0)
	ds_read2_b32 v[10:11], v27 offset0:33 offset1:41
	ds_read2_b32 v[12:13], v27 offset1:8
	ds_read2_b32 v[14:15], v27 offset0:66 offset1:74
	ds_read2_b32 v[16:17], v27 offset0:99 offset1:107
	ds_read2_b32 v[18:19], v27 offset0:132 offset1:140
	ds_read2_b32 v[20:21], v27 offset0:165 offset1:173
	ds_read2_b32 v[22:23], v27 offset0:198 offset1:206
	ds_read2_b32 v[52:53], v27 offset0:231 offset1:239
	v_mov_b32_e32 v5, v3
	v_lshl_add_u64 v[54:55], s[6:7], 0, v[4:5]
	s_waitcnt lgkmcnt(6)
	v_cvt_pk_bf16_f32 v6, v12, v10
	s_waitcnt lgkmcnt(4)
	v_cvt_pk_bf16_f32 v7, v14, v16
	s_waitcnt lgkmcnt(2)
	v_cvt_pk_bf16_f32 v8, v18, v20
	s_waitcnt lgkmcnt(0)
	v_cvt_pk_bf16_f32 v9, v22, v52
	v_lshl_add_u64 v[56:57], v[54:55], 0, v[56:57]
	v_or_b32_e32 v10, s0, v28
	global_store_dwordx4 v[56:57], v[6:9], off nt
	s_nop 1
	v_cvt_pk_bf16_f32 v6, v13, v11
	v_ashrrev_i32_e32 v11, 31, v10
	v_cvt_pk_bf16_f32 v7, v15, v17
	v_cvt_pk_bf16_f32 v8, v19, v21
	v_cvt_pk_bf16_f32 v9, v23, v53
	v_lshlrev_b64 v[10:11], 9, v[10:11]
	ds_read2_b32 v[12:13], v27 offset0:49 offset1:57
	ds_read2_b32 v[14:15], v27 offset0:16 offset1:24
	ds_read2_b32 v[16:17], v27 offset0:82 offset1:90
	ds_read2_b32 v[18:19], v27 offset0:115 offset1:123
	ds_read2_b32 v[20:21], v27 offset0:148 offset1:156
	ds_read2_b32 v[22:23], v27 offset0:181 offset1:189
	ds_read2_b32 v[52:53], v27 offset0:214 offset1:222
	ds_read2_b32 v[56:57], v27 offset0:247 offset1:255
	v_lshl_add_u64 v[10:11], v[54:55], 0, v[10:11]
	global_store_dwordx4 v[10:11], v[6:9], off nt
	v_or_b32_e32 v10, s0, v29
	v_ashrrev_i32_e32 v11, 31, v10
	v_lshlrev_b64 v[10:11], 9, v[10:11]
	s_waitcnt lgkmcnt(6)
	v_cvt_pk_bf16_f32 v6, v14, v12
	s_waitcnt lgkmcnt(4)
	v_cvt_pk_bf16_f32 v7, v16, v18
	s_waitcnt lgkmcnt(2)
	v_cvt_pk_bf16_f32 v8, v20, v22
	s_waitcnt lgkmcnt(0)
	v_cvt_pk_bf16_f32 v9, v52, v56
	v_lshl_add_u64 v[10:11], v[54:55], 0, v[10:11]
	global_store_dwordx4 v[10:11], v[6:9], off nt
	v_or_b32_e32 v10, s0, v30
	v_ashrrev_i32_e32 v11, 31, v10
	v_lshlrev_b64 v[10:11], 9, v[10:11]
	v_cvt_pk_bf16_f32 v6, v15, v13
	v_cvt_pk_bf16_f32 v7, v17, v19
	v_cvt_pk_bf16_f32 v8, v21, v23
	v_cvt_pk_bf16_f32 v9, v53, v57
	v_lshl_add_u64 v[10:11], v[54:55], 0, v[10:11]
	global_store_dwordx4 v[10:11], v[6:9], off nt
	s_waitcnt lgkmcnt(0)

; #define LAS __attribute__((address_space(3)))
; __device__ __forceinline__ void transpose_item(const float* W, int ldn, int k0, int n0, const float* gk, bf16_t* WT, int ldk, int drow0, LAS float* scr, int lane, const float* gn = nullptr) {
;     const float gnv = gn ? gn[lane & 31] : 1.f;
;     float wv[32];
; #pragma unroll
;     for (int i = 0; i < 32; ++i) wv[i] = W[(size_t)(k0 + 2 * i + (lane >> 5)) * ldn + n0 + (lane & 31)];
; __device__ __forceinline__ void convert_weights(const Params& p, LAS unsigned char* lds, int gw, int NGW, int wave, int lane) {
;     ...
;         r -= I_UP;
;         {
;             const int i = r / 1408, q = r % 1408, kb = q / 32, nb = q % 32;
;             transpose_item(p.w_out + (size_t)i * FF * D, D, 64 * kb, 32 * nb, nullptr, (bf16_t*)(p.ws + WS_WOUT) + (size_t)i * D * FF, FF, 32 * nb, scr, lane);
.LBB0_12:
	s_cmpk_gt_i32 s3, 0xff
	s_mov_b64 s[6:7], -1
	s_cbranch_scc0 .LBB0_54
	s_cmpk_gt_u32 s3, 0xcff
	s_cbranch_scc0 .LBB0_47
	s_cmpk_gt_u32 s3, 0x10ff
	s_cbranch_scc0 .LBB0_44
	s_cmpk_gt_u32 s3, 0x3cff
	s_cbranch_scc0 .LBB0_17
	s_add_i32 s0, s3, 0xc300
	s_and_b32 s6, s0, 0xffff
	s_mul_i32 s6, s6, 0xba2f
	s_lshr_b32 s7, s6, 26
	s_mul_i32 s6, s7, 0x580
	s_sub_i32 s0, s0, s6
	v_readlane_b32 s60, v251, 7
	s_and_b32 s0, s0, 0xffff
	s_mul_i32 s6, s7, 0xb00000
	v_readlane_b32 s74, v251, 21
	v_readlane_b32 s75, v251, 22
	s_add_u32 s13, s74, s6
	s_addc_u32 s15, s75, 0
	s_lshl_b32 s6, s0, 1
	s_lshl_b32 s0, s0, 5
	s_and_b32 s6, s6, 0xfc0
	s_and_b32 s0, s0, 0x3e0
	s_mul_i32 s7, s7, 0x580000
	v_readlane_b32 s12, v251, 41
	s_add_u32 s7, s12, s7
	v_readlane_b32 s12, v251, 43
	s_addc_u32 s12, s12, 0
	s_lshl_b32 s14, s0, 2
	s_add_u32 s14, s13, s14
	v_or_b32_e32 v5, s6, v1
	s_addc_u32 s15, s15, 0
	v_lshl_add_u64 v[6:7], s[14:15], 0, v[2:3]
	v_lshlrev_b32_e32 v8, 12, v5
	v_mov_b32_e32 v9, v3
	v_lshl_add_u64 v[6:7], v[6:7], 0, v[8:9]
	s_movk_i32 s13, 0x2000
	v_add_co_u32_e32 v8, vcc, s13, v6
	s_movk_i32 s13, 0x4000
	s_nop 0
	v_addc_co_u32_e32 v9, vcc, 0, v7, vcc
	v_add_co_u32_e32 v10, vcc, s13, v6
	s_movk_i32 s13, 0x6000
	s_nop 0
	v_addc_co_u32_e32 v11, vcc, 0, v7, vcc
	v_add_co_u32_e32 v12, vcc, s13, v6
	s_mov_b32 s13, 0x8000
	s_nop 0
	v_addc_co_u32_e32 v13, vcc, 0, v7, vcc
	v_add_co_u32_e32 v14, vcc, s13, v6
	s_mov_b32 s13, 0xa000
	s_nop 0
	v_addc_co_u32_e32 v15, vcc, 0, v7, vcc
	v_add_co_u32_e32 v16, vcc, s13, v6
	s_mov_b32 s13, 0xc000
	s_nop 0
	v_addc_co_u32_e32 v17, vcc, 0, v7, vcc
	v_add_co_u32_e32 v18, vcc, s13, v6
	s_mov_b32 s13, 0xe000
	s_nop 0
	v_addc_co_u32_e32 v19, vcc, 0, v7, vcc
	v_add_co_u32_e32 v20, vcc, s13, v6
	s_mov_b32 s13, 0x10000
	s_nop 0
	v_addc_co_u32_e32 v21, vcc, 0, v7, vcc
	global_load_dword v5, v[6:7], off
	global_load_dword v51, v[8:9], off
	global_load_dword v52, v[10:11], off
	global_load_dword v53, v[12:13], off
	global_load_dword v54, v[14:15], off
	global_load_dword v55, v[16:17], off
	global_load_dword v56, v[18:19], off
	global_load_dword v57, v[20:21], off
	v_add_co_u32_e32 v8, vcc, s13, v6
	s_lshl_b32 s6, s6, 1
	s_nop 0
	v_addc_co_u32_e32 v9, vcc, 0, v7, vcc
	v_add_co_u32_e32 v10, vcc, s51, v6
	s_add_u32 s6, s7, s6
	s_nop 0
	v_addc_co_u32_e32 v11, vcc, 0, v7, vcc
	v_add_co_u32_e32 v12, vcc, s53, v6
	s_addc_u32 s7, s12, 0
	s_nop 0
	v_addc_co_u32_e32 v13, vcc, 0, v7, vcc
	v_add_co_u32_e32 v14, vcc, s54, v6
	v_readlane_b32 s61, v251, 8
	s_nop 0
	v_addc_co_u32_e32 v15, vcc, 0, v7, vcc
	v_add_co_u32_e32 v16, vcc, s55, v6
	v_readlane_b32 s62, v251, 9
	s_nop 0
	v_addc_co_u32_e32 v17, vcc, 0, v7, vcc
	v_add_co_u32_e32 v18, vcc, s58, v6
	v_readlane_b32 s63, v251, 10
	s_nop 0
	v_addc_co_u32_e32 v19, vcc, 0, v7, vcc
	v_add_co_u32_e32 v20, vcc, s59, v6
	v_readlane_b32 s64, v251, 11
	s_nop 0
	v_addc_co_u32_e32 v21, vcc, 0, v7, vcc
	v_add_co_u32_e32 v22, vcc, s96, v6
	v_readlane_b32 s65, v251, 12
	s_nop 0
	v_addc_co_u32_e32 v23, vcc, 0, v7, vcc
	global_load_dword v58, v[8:9], off
	global_load_dword v59, v[10:11], off
	global_load_dword v60, v[12:13], off
	global_load_dword v61, v[14:15], off
	global_load_dword v62, v[16:17], off
	global_load_dword v63, v[18:19], off
	global_load_dword v64, v[20:21], off
	global_load_dword v65, v[22:23], off
	v_add_co_u32_e32 v8, vcc, s97, v6
	v_readlane_b32 s66, v251, 13
	s_nop 0
	v_addc_co_u32_e32 v9, vcc, 0, v7, vcc
	v_add_co_u32_e32 v10, vcc, s4, v6
	v_readlane_b32 s67, v251, 14
	s_nop 0
	v_addc_co_u32_e32 v11, vcc, 0, v7, vcc
	v_add_co_u32_e32 v12, vcc, s5, v6
	v_readlane_b32 s68, v251, 15
	s_nop 0
	v_addc_co_u32_e32 v13, vcc, 0, v7, vcc
	v_add_co_u32_e32 v14, vcc, s19, v6
	v_readlane_b32 s69, v251, 16
	s_nop 0
	v_addc_co_u32_e32 v15, vcc, 0, v7, vcc
	v_add_co_u32_e32 v16, vcc, s20, v6
	v_readlane_b32 s70, v251, 17
	s_nop 0
	v_addc_co_u32_e32 v17, vcc, 0, v7, vcc
	v_add_co_u32_e32 v18, vcc, s21, v6
	v_readlane_b32 s71, v251, 18
	s_nop 0
	v_addc_co_u32_e32 v19, vcc, 0, v7, vcc
	v_add_co_u32_e32 v20, vcc, s22, v6
	v_readlane_b32 s72, v251, 19
	s_nop 0
	v_addc_co_u32_e32 v21, vcc, 0, v7, vcc
	v_add_co_u32_e32 v22, vcc, s43, v6
	v_readlane_b32 s73, v251, 20
	s_nop 0
	v_addc_co_u32_e32 v23, vcc, 0, v7, vcc
	global_load_dword v66, v[8:9], off
	global_load_dword v67, v[10:11], off
	global_load_dword v68, v[12:13], off
	global_load_dword v69, v[14:15], off
	global_load_dword v70, v[16:17], off
	global_load_dword v71, v[18:19], off
	global_load_dword v72, v[20:21], off
	s_nop 0
	global_load_dword v22, v[22:23], off
	v_add_co_u32_e32 v8, vcc, s44, v6
	s_nop 1
	v_addc_co_u32_e32 v9, vcc, 0, v7, vcc
	v_add_co_u32_e32 v10, vcc, s45, v6
	s_nop 1
	v_addc_co_u32_e32 v11, vcc, 0, v7, vcc
	v_add_co_u32_e32 v12, vcc, s46, v6
	s_nop 1
	v_addc_co_u32_e32 v13, vcc, 0, v7, vcc
	v_add_co_u32_e32 v14, vcc, s47, v6
	s_nop 1
	v_addc_co_u32_e32 v15, vcc, 0, v7, vcc
	v_add_co_u32_e32 v16, vcc, s48, v6
	s_nop 1
	v_addc_co_u32_e32 v17, vcc, 0, v7, vcc
	v_add_co_u32_e32 v18, vcc, s49, v6
	s_nop 1
	v_addc_co_u32_e32 v19, vcc, 0, v7, vcc
	v_add_co_u32_e32 v20, vcc, s50, v6
	s_nop 1
	v_addc_co_u32_e32 v21, vcc, 0, v7, vcc
	v_add_co_u32_e32 v6, vcc, s76, v6
	s_nop 1
	v_addc_co_u32_e32 v7, vcc, 0, v7, vcc
	global_load_dword v8, v[8:9], off
	s_nop 0
	global_load_dword v9, v[10:11], off
	s_nop 0
	global_load_dword v10, v[12:13], off
	global_load_dword v11, v[14:15], off
	s_nop 0
	global_load_dword v12, v[16:17], off
	global_load_dword v13, v[18:19], off
	global_load_dword v14, v[20:21], off
	s_nop 0
	global_load_dword v6, v[6:7], off
	s_waitcnt vmcnt(30)
; #define LAS __attribute__((address_space(3)))
; __device__ __forceinline__ unsigned cvt_pk_bf16(float lo, float hi) { const f32x2 v = {lo, hi}; const bf16x2_t b = __builtin_convertvector(v, bf16x2_t); return __builtin_bit_cast(unsigned, b); }
; __device__ __forceinline__ void transpose_item(const float* W, int ldn, int k0, int n0, const float* gk, bf16_t* WT, int ldk, int drow0, LAS float* scr, int lane, const float* gn = nullptr) {
;     ...
;     for (int i = 0; i < 32; ++i) { const int kk = 2 * i + (lane >> 5); float v = wv[i] * gnv; if (gk) v *= gk[k0 + kk]; scr[kk * 33 + (lane & 31)] = v; }
;     asm volatile("s_waitcnt lgkmcnt(0)" ::: "memory");
;     const int c = lane & 7;
; #pragma unroll
;     for (int j = 0; j < 4; ++j) { const int n = (lane >> 3) + 8 * j; const LAS float* s = scr + (8 * c) * 33 + n;
;         u32x4 o; o.x = cvt_pk_bf16(s[0 * 33], s[1 * 33]); o.y = cvt_pk_bf16(s[2 * 33], s[3 * 33]); o.z = cvt_pk_bf16(s[4 * 33], s[5 * 33]); o.w = cvt_pk_bf16(s[6 * 33], s[7 * 33]);
;         *(u32x4*)(WT + (size_t)(drow0 + n) * ldk + k0 + 8 * c) = o; }
;     asm volatile("s_waitcnt lgkmcnt(0)" ::: "memory");
	ds_write2_b32 v25, v5, v51 offset1:66
	s_waitcnt vmcnt(28)
	ds_write2_b32 v25, v52, v53 offset0:132 offset1:198
	s_waitcnt vmcnt(26)
	ds_write2_b32 v38, v54, v55 offset0:8 offset1:74
	s_waitcnt vmcnt(24)
	ds_write2_b32 v38, v56, v57 offset0:140 offset1:206
	s_waitcnt vmcnt(22)
	ds_write2_b32 v39, v58, v59 offset0:16 offset1:82
	s_waitcnt vmcnt(20)
	ds_write2_b32 v39, v60, v61 offset0:148 offset1:214
	s_waitcnt vmcnt(18)
	ds_write2_b32 v40, v62, v63 offset0:24 offset1:90
	s_waitcnt vmcnt(16)
	ds_write2_b32 v40, v64, v65 offset0:156 offset1:222
	s_waitcnt vmcnt(14)
	ds_write2_b32 v41, v66, v67 offset0:32 offset1:98
	s_waitcnt vmcnt(12)
	ds_write2_b32 v41, v68, v69 offset0:164 offset1:230
	s_waitcnt vmcnt(10)
	ds_write2_b32 v42, v70, v71 offset0:40 offset1:106
	s_waitcnt vmcnt(8)
	ds_write2_b32 v42, v72, v22 offset0:172 offset1:238
	s_waitcnt vmcnt(6)
	ds_write2_b32 v43, v8, v9 offset0:48 offset1:114
	s_waitcnt vmcnt(4)
	ds_write2_b32 v43, v10, v11 offset0:180 offset1:246
	s_waitcnt vmcnt(2)
	ds_write2_b32 v44, v12, v13 offset0:56 offset1:122
	s_waitcnt vmcnt(0)
	ds_write2_b32 v44, v14, v6 offset0:188 offset1:254
	s_waitcnt lgkmcnt(0)
	ds_read2_b32 v[10:11], v27 offset0:33 offset1:41
	ds_read2_b32 v[12:13], v27 offset1:8
	ds_read2_b32 v[14:15], v27 offset0:66 offset1:74
	ds_read2_b32 v[16:17], v27 offset0:99 offset1:107
	ds_read2_b32 v[18:19], v27 offset0:132 offset1:140
	ds_read2_b32 v[20:21], v27 offset0:165 offset1:173
	ds_read2_b32 v[22:23], v27 offset0:198 offset1:206
	ds_read2_b32 v[52:53], v27 offset0:231 offset1:239
	v_mov_b32_e32 v5, v3
	v_lshl_add_u64 v[54:55], s[6:7], 0, v[4:5]
	v_or_b32_e32 v5, s0, v26
	v_mul_u32_u24_e32 v5, 0xb00, v5
	v_lshlrev_b32_e32 v56, 1, v5
	v_mov_b32_e32 v57, v3
	s_waitcnt lgkmcnt(6)
	v_cvt_pk_bf16_f32 v6, v12, v10
	s_waitcnt lgkmcnt(4)
	v_cvt_pk_bf16_f32 v7, v14, v16
	s_waitcnt lgkmcnt(2)
	v_cvt_pk_bf16_f32 v8, v18, v20
	s_waitcnt lgkmcnt(0)
	v_cvt_pk_bf16_f32 v9, v22, v52
	v_lshl_add_u64 v[56:57], v[54:55], 0, v[56:57]
	global_store_dwordx4 v[56:57], v[6:9], off nt
	v_or_b32_e32 v5, s0, v28
	v_mul_u32_u24_e32 v5, 0xb00, v5
	v_cvt_pk_bf16_f32 v6, v13, v11
	v_cvt_pk_bf16_f32 v7, v15, v17
	v_cvt_pk_bf16_f32 v8, v19, v21
	v_cvt_pk_bf16_f32 v9, v23, v53
	ds_read2_b32 v[12:13], v27 offset0:16 offset1:24
	ds_read2_b32 v[14:15], v27 offset0:49 offset1:57
	ds_read2_b32 v[16:17], v27 offset0:82 offset1:90
	ds_read2_b32 v[18:19], v27 offset0:115 offset1:123
	ds_read2_b32 v[20:21], v27 offset0:148 offset1:156
	ds_read2_b32 v[22:23], v27 offset0:181 offset1:189
	ds_read2_b32 v[52:53], v27 offset0:214 offset1:222
	ds_read2_b32 v[56:57], v27 offset0:247 offset1:255
	v_lshlrev_b32_e32 v10, 1, v5
	v_mov_b32_e32 v11, v3
	v_or_b32_e32 v5, s0, v29
	v_lshl_add_u64 v[10:11], v[54:55], 0, v[10:11]
	v_mul_u32_u24_e32 v5, 0xb00, v5
	global_store_dwordx4 v[10:11], v[6:9], off nt
	v_lshlrev_b32_e32 v10, 1, v5
	v_mov_b32_e32 v11, v3
	v_or_b32_e32 v5, s0, v30
	s_waitcnt lgkmcnt(6)
	v_cvt_pk_bf16_f32 v6, v12, v14
	s_waitcnt lgkmcnt(4)
	v_cvt_pk_bf16_f32 v7, v16, v18
	s_waitcnt lgkmcnt(2)
	v_cvt_pk_bf16_f32 v8, v20, v22
	s_waitcnt lgkmcnt(0)
	v_cvt_pk_bf16_f32 v9, v52, v56
	v_lshl_add_u64 v[10:11], v[54:55], 0, v[10:11]
	v_mul_u32_u24_e32 v5, 0xb00, v5
	global_store_dwordx4 v[10:11], v[6:9], off nt
	v_lshlrev_b32_e32 v10, 1, v5
	v_mov_b32_e32 v11, v3
	v_cvt_pk_bf16_f32 v6, v13, v15
	v_cvt_pk_bf16_f32 v7, v17, v19
	v_cvt_pk_bf16_f32 v8, v21, v23
	v_cvt_pk_bf16_f32 v9, v53, v57
	v_lshl_add_u64 v[10:11], v[54:55], 0, v[10:11]
	global_store_dwordx4 v[10:11], v[6:9], off nt
	s_waitcnt lgkmcnt(0)
	s_mov_b64 s[6:7], 0

; #define LAS __attribute__((address_space(3)))
; __device__ __forceinline__ unsigned cvt_pk_bf16(float lo, float hi) { const f32x2 v = {lo, hi}; const bf16x2_t b = __builtin_convertvector(v, bf16x2_t); return __builtin_bit_cast(unsigned, b); }
; __device__ __forceinline__ void transpose_item(const float* W, int ldn, int k0, int n0, const float* gk, bf16_t* WT, int ldk, int drow0, LAS float* scr, int lane, const float* gn = nullptr) {
;     ...
;     for (int i = 0; i < 32; ++i) { const int kk = 2 * i + (lane >> 5); float v = wv[i] * gnv; if (gk) v *= gk[k0 + kk]; scr[kk * 33 + (lane & 31)] = v; }
;     asm volatile("s_waitcnt lgkmcnt(0)" ::: "memory");
;     const int c = lane & 7;
; #pragma unroll
;     for (int j = 0; j < 4; ++j) { const int n = (lane >> 3) + 8 * j; const LAS float* s = scr + (8 * c) * 33 + n;
;         u32x4 o; o.x = cvt_pk_bf16(s[0 * 33], s[1 * 33]); o.y = cvt_pk_bf16(s[2 * 33], s[3 * 33]); o.z = cvt_pk_bf16(s[4 * 33], s[5 * 33]); o.w = cvt_pk_bf16(s[6 * 33], s[7 * 33]);
;         *(u32x4*)(WT + (size_t)(drow0 + n) * ldk + k0 + 8 * c) = o; }
;     asm volatile("s_waitcnt lgkmcnt(0)" ::: "memory");
; __device__ __forceinline__ void convert_weights(const Params& p, LAS unsigned char* lds, int gw, int NGW, int wave, int lane) {
;     ...
;             const int i = r / 2816, q = r % 2816, isval = q / 1408, q2 = q % 1408, kb = q2 / 88, nb = q2 % 88, f0 = 32 * nb;
;             const float* W = (isval ? p.w_val : p.w_gate) + (size_t)i * D * FF;
;             transpose_item(W, FF, 64 * kb, f0, p.ffn_norm + (size_t)i * D, (bf16_t*)(p.ws + WS_WUP) + (size_t)i * 5632 * D, D, 256 * (f0 >> 7) + 128 * isval + (f0 & 127), scr, lane);
.LBB0_42:
	v_readlane_b32 s6, v251, 45
	s_add_u32 s6, s6, s80
	v_readlane_b32 s7, v251, 47
	s_addc_u32 s7, s7, 0
	s_lshl_b32 s12, s79, 6
	s_and_b32 s12, s12, 0x1f00
	s_cmpk_gt_u32 s16, 0x57f
	s_waitcnt vmcnt(3)
	v_add_u32_e32 v5, 0xa00, v14
	s_cselect_b32 s13, 0x80, 0
	ds_write2_b32 v5, v8, v9 offset0:86 offset1:152
	s_or_b32 s12, s12, s13
	s_and_b32 s0, s0, 0x60
	s_waitcnt lgkmcnt(0)
	s_or_b32 s0, s12, s0
	s_lshl_b32 s12, s17, 1
	ds_read2_b32 v[10:11], v27 offset0:33 offset1:41
	ds_read2_b32 v[12:13], v27 offset1:8
	ds_read2_b32 v[14:15], v27 offset0:66 offset1:74
	ds_read2_b32 v[16:17], v27 offset0:99 offset1:107
	ds_read2_b32 v[18:19], v27 offset0:132 offset1:140
	ds_read2_b32 v[20:21], v27 offset0:165 offset1:173
	ds_read2_b32 v[22:23], v27 offset0:198 offset1:206
	ds_read2_b32 v[52:53], v27 offset0:231 offset1:239
	s_add_u32 s6, s6, s12
	s_addc_u32 s7, s7, 0
	v_mov_b32_e32 v5, v3
	v_lshl_add_u64 v[54:55], s[6:7], 0, v[4:5]
	v_or_b32_e32 v5, s0, v26
	v_lshlrev_b32_e32 v56, 11, v5
	v_mov_b32_e32 v57, v3
	s_waitcnt vmcnt(1) lgkmcnt(6)
	v_cvt_pk_bf16_f32 v6, v12, v10
	s_waitcnt vmcnt(0) lgkmcnt(4)
	v_cvt_pk_bf16_f32 v7, v14, v16
	s_waitcnt lgkmcnt(2)
	v_cvt_pk_bf16_f32 v8, v18, v20
	s_waitcnt lgkmcnt(0)
	v_cvt_pk_bf16_f32 v9, v22, v52
	v_lshl_add_u64 v[56:57], v[54:55], 0, v[56:57]
	global_store_dwordx4 v[56:57], v[6:9], off nt
	v_or_b32_e32 v5, s0, v28
	v_lshlrev_b32_e32 v10, 11, v5
	v_cvt_pk_bf16_f32 v6, v13, v11
	v_cvt_pk_bf16_f32 v7, v15, v17
	v_cvt_pk_bf16_f32 v8, v19, v21
	v_cvt_pk_bf16_f32 v9, v23, v53
	ds_read2_b32 v[12:13], v27 offset0:49 offset1:57
	ds_read2_b32 v[14:15], v27 offset0:16 offset1:24
	ds_read2_b32 v[16:17], v27 offset0:82 offset1:90
	ds_read2_b32 v[18:19], v27 offset0:115 offset1:123
	ds_read2_b32 v[20:21], v27 offset0:148 offset1:156
	ds_read2_b32 v[22:23], v27 offset0:181 offset1:189
	ds_read2_b32 v[52:53], v27 offset0:214 offset1:222
	ds_read2_b32 v[56:57], v27 offset0:247 offset1:255
	v_mov_b32_e32 v11, v3
	v_lshl_add_u64 v[10:11], v[54:55], 0, v[10:11]
	v_or_b32_e32 v5, s0, v29
	global_store_dwordx4 v[10:11], v[6:9], off nt
	v_lshlrev_b32_e32 v10, 11, v5
	v_mov_b32_e32 v11, v3
	s_waitcnt lgkmcnt(6)
	v_cvt_pk_bf16_f32 v6, v14, v12
	s_waitcnt lgkmcnt(4)
	v_cvt_pk_bf16_f32 v7, v16, v18
	s_waitcnt lgkmcnt(2)
	v_cvt_pk_bf16_f32 v8, v20, v22
	s_waitcnt lgkmcnt(0)
	v_cvt_pk_bf16_f32 v9, v52, v56
	v_lshl_add_u64 v[10:11], v[54:55], 0, v[10:11]
	v_or_b32_e32 v5, s0, v30
	global_store_dwordx4 v[10:11], v[6:9], off nt
	v_lshlrev_b32_e32 v10, 11, v5
	v_mov_b32_e32 v11, v3
	v_cvt_pk_bf16_f32 v6, v15, v13
	v_cvt_pk_bf16_f32 v7, v17, v19
	v_cvt_pk_bf16_f32 v8, v21, v23
	v_cvt_pk_bf16_f32 v9, v53, v57
	v_lshl_add_u64 v[10:11], v[54:55], 0, v[10:11]
	global_store_dwordx4 v[10:11], v[6:9], off nt
	s_waitcnt lgkmcnt(0)
	v_readlane_b32 s80, v251, 23
	v_readlane_b32 s81, v251, 24
	v_readlane_b32 s82, v251, 25
	v_readlane_b32 s83, v251, 26
	v_readlane_b32 s84, v251, 27
	v_readlane_b32 s85, v251, 28
	v_readlane_b32 s86, v251, 29
	v_readlane_b32 s87, v251, 30
	v_readlane_b32 s88, v251, 31
	v_readlane_b32 s89, v251, 32
	v_readlane_b32 s90, v251, 33
	v_readlane_b32 s91, v251, 34
	v_readlane_b32 s92, v251, 35
	v_readlane_b32 s93, v251, 36
	v_readlane_b32 s94, v251, 37
	v_readlane_b32 s95, v251, 38

; #define LAS __attribute__((address_space(3)))
; __device__ __forceinline__ void transpose_item(const float* W, int ldn, int k0, int n0, const float* gk, bf16_t* WT, int ldk, int drow0, LAS float* scr, int lane, const float* gn = nullptr) {
;     const float gnv = gn ? gn[lane & 31] : 1.f;
;     float wv[32];
; #pragma unroll
;     for (int i = 0; i < 32; ++i) wv[i] = W[(size_t)(k0 + 2 * i + (lane >> 5)) * ldn + n0 + (lane & 31)];
; __device__ __forceinline__ void convert_weights(const Params& p, LAS unsigned char* lds, int gw, int NGW, int wave, int lane) {
;     ...
;         r -= I_QKV;
;         if (r < I_WO) {
;             const int j = r / 512, q = r % 512, kb = q / 32, nb = q % 32;
;             transpose_item(p.wo + (size_t)j * D * D, D, 64 * kb, 32 * nb, nullptr, (bf16_t*)(p.ws + WS_WO) + (size_t)j * D * D, D, 32 * nb, scr, lane);
.LBB0_44:
	s_andn2_b64 vcc, exec, s[6:7]
	s_cbranch_vccnz .LBB0_46
	s_add_i32 s0, s3, 0xfffff300
	s_lshr_b32 s0, s0, 9
	v_readlane_b32 s60, v251, 7
	s_lshl_b64 s[6:7], s[0:1], 22
	v_readlane_b32 s64, v251, 11
	v_readlane_b32 s65, v251, 12
	s_add_u32 s14, s64, s6
	s_addc_u32 s15, s65, s7
	s_and_b32 s7, s39, 0x3c0
	s_and_b32 s6, s41, 0x3e0
	s_lshl_b64 s[12:13], s[0:1], 21
	s_add_u32 s0, s23, s12
	s_addc_u32 s12, s30, s13
	s_lshl_b32 s13, s6, 2
	s_add_u32 s14, s14, s13
	v_or_b32_e32 v5, s7, v1
	s_addc_u32 s15, s15, 0
	v_lshl_add_u64 v[6:7], s[14:15], 0, v[2:3]
	v_lshlrev_b32_e32 v8, 12, v5
	v_mov_b32_e32 v9, v3
	v_lshl_add_u64 v[6:7], v[6:7], 0, v[8:9]
	s_movk_i32 s13, 0x2000
	v_add_co_u32_e32 v8, vcc, s13, v6
	s_movk_i32 s13, 0x4000
	s_nop 0
	v_addc_co_u32_e32 v9, vcc, 0, v7, vcc
	v_add_co_u32_e32 v10, vcc, s13, v6
	s_movk_i32 s13, 0x6000
	s_nop 0
	v_addc_co_u32_e32 v11, vcc, 0, v7, vcc
	v_add_co_u32_e32 v12, vcc, s13, v6
	s_mov_b32 s13, 0x8000
	s_nop 0
	v_addc_co_u32_e32 v13, vcc, 0, v7, vcc
	v_add_co_u32_e32 v14, vcc, s13, v6
	s_mov_b32 s13, 0xa000
	s_nop 0
	v_addc_co_u32_e32 v15, vcc, 0, v7, vcc
	v_add_co_u32_e32 v16, vcc, s13, v6
	s_mov_b32 s13, 0xc000
	s_nop 0
	v_addc_co_u32_e32 v17, vcc, 0, v7, vcc
	v_add_co_u32_e32 v18, vcc, s13, v6
	s_mov_b32 s13, 0xe000
	s_nop 0
	v_addc_co_u32_e32 v19, vcc, 0, v7, vcc
	v_add_co_u32_e32 v20, vcc, s13, v6
	s_mov_b32 s13, 0x10000
	s_nop 0
	v_addc_co_u32_e32 v21, vcc, 0, v7, vcc
	global_load_dword v5, v[6:7], off
	global_load_dword v51, v[8:9], off
	global_load_dword v52, v[10:11], off
	global_load_dword v53, v[12:13], off
	global_load_dword v54, v[14:15], off
	global_load_dword v55, v[16:17], off
	global_load_dword v56, v[18:19], off
	global_load_dword v57, v[20:21], off
	v_add_co_u32_e32 v8, vcc, s13, v6
	s_lshl_b32 s7, s7, 1
	s_nop 0
	v_addc_co_u32_e32 v9, vcc, 0, v7, vcc
	v_add_co_u32_e32 v10, vcc, s51, v6
	s_add_u32 s14, s0, s7
	s_nop 0
	v_addc_co_u32_e32 v11, vcc, 0, v7, vcc
	v_add_co_u32_e32 v12, vcc, s53, v6
	s_addc_u32 s15, s12, 0
	s_nop 0
	v_addc_co_u32_e32 v13, vcc, 0, v7, vcc
	v_add_co_u32_e32 v14, vcc, s54, v6
	v_readlane_b32 s61, v251, 8
	s_nop 0
	v_addc_co_u32_e32 v15, vcc, 0, v7, vcc
	v_add_co_u32_e32 v16, vcc, s55, v6
	v_readlane_b32 s62, v251, 9
	s_nop 0
	v_addc_co_u32_e32 v17, vcc, 0, v7, vcc
	v_add_co_u32_e32 v18, vcc, s58, v6
	v_readlane_b32 s63, v251, 10
	s_nop 0
	v_addc_co_u32_e32 v19, vcc, 0, v7, vcc
	v_add_co_u32_e32 v20, vcc, s59, v6
	v_readlane_b32 s66, v251, 13
	s_nop 0
	v_addc_co_u32_e32 v21, vcc, 0, v7, vcc
	v_add_co_u32_e32 v22, vcc, s96, v6
	v_readlane_b32 s67, v251, 14
	s_nop 0
	v_addc_co_u32_e32 v23, vcc, 0, v7, vcc
	global_load_dword v58, v[8:9], off
	global_load_dword v59, v[10:11], off
	global_load_dword v60, v[12:13], off
	global_load_dword v61, v[14:15], off
	global_load_dword v62, v[16:17], off
	global_load_dword v63, v[18:19], off
	global_load_dword v64, v[20:21], off
	global_load_dword v65, v[22:23], off
	v_add_co_u32_e32 v8, vcc, s97, v6
	v_readlane_b32 s68, v251, 15
	s_nop 0
	v_addc_co_u32_e32 v9, vcc, 0, v7, vcc
	v_add_co_u32_e32 v10, vcc, s4, v6
	v_readlane_b32 s69, v251, 16
	s_nop 0
	v_addc_co_u32_e32 v11, vcc, 0, v7, vcc
	v_add_co_u32_e32 v12, vcc, s5, v6
	v_readlane_b32 s70, v251, 17
	s_nop 0
	v_addc_co_u32_e32 v13, vcc, 0, v7, vcc
	v_add_co_u32_e32 v14, vcc, s19, v6
	v_readlane_b32 s71, v251, 18
	s_nop 0
	v_addc_co_u32_e32 v15, vcc, 0, v7, vcc
	v_add_co_u32_e32 v16, vcc, s20, v6
	v_readlane_b32 s72, v251, 19
	s_nop 0
	v_addc_co_u32_e32 v17, vcc, 0, v7, vcc
	v_add_co_u32_e32 v18, vcc, s21, v6
	v_readlane_b32 s73, v251, 20
	s_nop 0
	v_addc_co_u32_e32 v19, vcc, 0, v7, vcc
	v_add_co_u32_e32 v20, vcc, s22, v6
	v_readlane_b32 s74, v251, 21
	s_nop 0
	v_addc_co_u32_e32 v21, vcc, 0, v7, vcc
	v_add_co_u32_e32 v22, vcc, s43, v6
	v_readlane_b32 s75, v251, 22
	s_nop 0
	v_addc_co_u32_e32 v23, vcc, 0, v7, vcc
	global_load_dword v66, v[8:9], off
	global_load_dword v67, v[10:11], off
	global_load_dword v68, v[12:13], off
	global_load_dword v69, v[14:15], off
	global_load_dword v70, v[16:17], off
	global_load_dword v71, v[18:19], off
	global_load_dword v72, v[20:21], off
	s_nop 0
	global_load_dword v22, v[22:23], off
	v_add_co_u32_e32 v8, vcc, s44, v6
	s_nop 1
	v_addc_co_u32_e32 v9, vcc, 0, v7, vcc
	v_add_co_u32_e32 v10, vcc, s45, v6
	s_nop 1
	v_addc_co_u32_e32 v11, vcc, 0, v7, vcc
	v_add_co_u32_e32 v12, vcc, s46, v6
	s_nop 1
	v_addc_co_u32_e32 v13, vcc, 0, v7, vcc
	v_add_co_u32_e32 v14, vcc, s47, v6
	s_nop 1
	v_addc_co_u32_e32 v15, vcc, 0, v7, vcc
	v_add_co_u32_e32 v16, vcc, s48, v6
	s_nop 1
	v_addc_co_u32_e32 v17, vcc, 0, v7, vcc
	v_add_co_u32_e32 v18, vcc, s49, v6
	s_nop 1
	v_addc_co_u32_e32 v19, vcc, 0, v7, vcc
	v_add_co_u32_e32 v20, vcc, s50, v6
	s_nop 1
	v_addc_co_u32_e32 v21, vcc, 0, v7, vcc
	v_add_co_u32_e32 v6, vcc, s76, v6
	s_nop 1
	v_addc_co_u32_e32 v7, vcc, 0, v7, vcc
	global_load_dword v8, v[8:9], off
	s_nop 0
	global_load_dword v9, v[10:11], off
	s_nop 0
	global_load_dword v10, v[12:13], off
	global_load_dword v11, v[14:15], off
	s_nop 0
	global_load_dword v12, v[16:17], off
	global_load_dword v13, v[18:19], off
	global_load_dword v14, v[20:21], off
	s_nop 0
	global_load_dword v6, v[6:7], off
	s_waitcnt vmcnt(30)
; #define LAS __attribute__((address_space(3)))
; __device__ __forceinline__ unsigned cvt_pk_bf16(float lo, float hi) { const f32x2 v = {lo, hi}; const bf16x2_t b = __builtin_convertvector(v, bf16x2_t); return __builtin_bit_cast(unsigned, b); }
; __device__ __forceinline__ void transpose_item(const float* W, int ldn, int k0, int n0, const float* gk, bf16_t* WT, int ldk, int drow0, LAS float* scr, int lane, const float* gn = nullptr) {
;     ...
;     for (int i = 0; i < 32; ++i) { const int kk = 2 * i + (lane >> 5); float v = wv[i] * gnv; if (gk) v *= gk[k0 + kk]; scr[kk * 33 + (lane & 31)] = v; }
;     asm volatile("s_waitcnt lgkmcnt(0)" ::: "memory");
;     const int c = lane & 7;
; #pragma unroll
;     for (int j = 0; j < 4; ++j) { const int n = (lane >> 3) + 8 * j; const LAS float* s = scr + (8 * c) * 33 + n;
;         u32x4 o; o.x = cvt_pk_bf16(s[0 * 33], s[1 * 33]); o.y = cvt_pk_bf16(s[2 * 33], s[3 * 33]); o.z = cvt_pk_bf16(s[4 * 33], s[5 * 33]); o.w = cvt_pk_bf16(s[6 * 33], s[7 * 33]);
;         *(u32x4*)(WT + (size_t)(drow0 + n) * ldk + k0 + 8 * c) = o; }
;     asm volatile("s_waitcnt lgkmcnt(0)" ::: "memory");
	ds_write2_b32 v25, v5, v51 offset1:66
	s_waitcnt vmcnt(28)
	ds_write2_b32 v25, v52, v53 offset0:132 offset1:198
	s_waitcnt vmcnt(26)
	ds_write2_b32 v38, v54, v55 offset0:8 offset1:74
	s_waitcnt vmcnt(24)
	ds_write2_b32 v38, v56, v57 offset0:140 offset1:206
	s_waitcnt vmcnt(22)
	ds_write2_b32 v39, v58, v59 offset0:16 offset1:82
	s_waitcnt vmcnt(20)
	ds_write2_b32 v39, v60, v61 offset0:148 offset1:214
	s_waitcnt vmcnt(18)
	ds_write2_b32 v40, v62, v63 offset0:24 offset1:90
	s_waitcnt vmcnt(16)
	ds_write2_b32 v40, v64, v65 offset0:156 offset1:222
	s_waitcnt vmcnt(14)
	ds_write2_b32 v41, v66, v67 offset0:32 offset1:98
	s_waitcnt vmcnt(12)
	ds_write2_b32 v41, v68, v69 offset0:164 offset1:230
	s_waitcnt vmcnt(10)
	ds_write2_b32 v42, v70, v71 offset0:40 offset1:106
	s_waitcnt vmcnt(8)
	ds_write2_b32 v42, v72, v22 offset0:172 offset1:238
	s_waitcnt vmcnt(6)
	ds_write2_b32 v43, v8, v9 offset0:48 offset1:114
	s_waitcnt vmcnt(4)
	ds_write2_b32 v43, v10, v11 offset0:180 offset1:246
	s_waitcnt vmcnt(2)
	ds_write2_b32 v44, v12, v13 offset0:56 offset1:122
	s_waitcnt vmcnt(0)
	ds_write2_b32 v44, v14, v6 offset0:188 offset1:254
	s_waitcnt lgkmcnt(0)
	ds_read2_b32 v[10:11], v27 offset0:33 offset1:41
	ds_read2_b32 v[12:13], v27 offset1:8
	ds_read2_b32 v[14:15], v27 offset0:66 offset1:74
	ds_read2_b32 v[16:17], v27 offset0:99 offset1:107
	ds_read2_b32 v[18:19], v27 offset0:132 offset1:140
	ds_read2_b32 v[20:21], v27 offset0:165 offset1:173
	ds_read2_b32 v[22:23], v27 offset0:198 offset1:206
	ds_read2_b32 v[52:53], v27 offset0:231 offset1:239
	v_mov_b32_e32 v5, v3
	v_lshl_add_u64 v[54:55], s[14:15], 0, v[4:5]
	v_or_b32_e32 v5, s6, v26
	v_lshlrev_b32_e32 v56, 11, v5
	v_mov_b32_e32 v57, v3
	s_waitcnt lgkmcnt(6)
	v_cvt_pk_bf16_f32 v6, v12, v10
	s_waitcnt lgkmcnt(4)
	v_cvt_pk_bf16_f32 v7, v14, v16
	s_waitcnt lgkmcnt(2)
	v_cvt_pk_bf16_f32 v8, v18, v20
	s_waitcnt lgkmcnt(0)
	v_cvt_pk_bf16_f32 v9, v22, v52
	v_lshl_add_u64 v[56:57], v[54:55], 0, v[56:57]
	global_store_dwordx4 v[56:57], v[6:9], off nt
	v_or_b32_e32 v5, s6, v28
	v_lshlrev_b32_e32 v10, 11, v5
	v_cvt_pk_bf16_f32 v6, v13, v11
	v_cvt_pk_bf16_f32 v7, v15, v17
	v_cvt_pk_bf16_f32 v8, v19, v21
	v_cvt_pk_bf16_f32 v9, v23, v53
	ds_read2_b32 v[12:13], v27 offset0:49 offset1:57
	ds_read2_b32 v[14:15], v27 offset0:16 offset1:24
	ds_read2_b32 v[16:17], v27 offset0:82 offset1:90
	ds_read2_b32 v[18:19], v27 offset0:115 offset1:123
	ds_read2_b32 v[20:21], v27 offset0:148 offset1:156
	ds_read2_b32 v[22:23], v27 offset0:181 offset1:189
	ds_read2_b32 v[52:53], v27 offset0:214 offset1:222
	ds_read2_b32 v[56:57], v27 offset0:247 offset1:255
	v_mov_b32_e32 v11, v3
	v_lshl_add_u64 v[10:11], v[54:55], 0, v[10:11]
	v_or_b32_e32 v5, s6, v29
	global_store_dwordx4 v[10:11], v[6:9], off nt
	v_lshlrev_b32_e32 v10, 11, v5
	v_mov_b32_e32 v11, v3
	s_waitcnt lgkmcnt(6)
	v_cvt_pk_bf16_f32 v6, v14, v12
	s_waitcnt lgkmcnt(4)
	v_cvt_pk_bf16_f32 v7, v16, v18
	s_waitcnt lgkmcnt(2)
	v_cvt_pk_bf16_f32 v8, v20, v22
	s_waitcnt lgkmcnt(0)
	v_cvt_pk_bf16_f32 v9, v52, v56
	v_lshl_add_u64 v[10:11], v[54:55], 0, v[10:11]
	v_or_b32_e32 v5, s6, v30
	global_store_dwordx4 v[10:11], v[6:9], off nt
	v_lshlrev_b32_e32 v10, 11, v5
	v_mov_b32_e32 v11, v3
	v_cvt_pk_bf16_f32 v6, v15, v13
	v_cvt_pk_bf16_f32 v7, v17, v19
	v_cvt_pk_bf16_f32 v8, v21, v23
	v_cvt_pk_bf16_f32 v9, v53, v57
	v_lshl_add_u64 v[10:11], v[54:55], 0, v[10:11]
	global_store_dwordx4 v[10:11], v[6:9], off nt
	s_waitcnt lgkmcnt(0)

; #define LAS __attribute__((address_space(3)))
; __device__ __forceinline__ void transpose_item(const float* W, int ldn, int k0, int n0, const float* gk, bf16_t* WT, int ldk, int drow0, LAS float* scr, int lane, const float* gn = nullptr) {
;     const float gnv = gn ? gn[lane & 31] : 1.f;
;     float wv[32];
; #pragma unroll
;     for (int i = 0; i < 32; ++i) wv[i] = W[(size_t)(k0 + 2 * i + (lane >> 5)) * ldn + n0 + (lane & 31)];
; __device__ __forceinline__ void convert_weights(const Params& p, LAS unsigned char* lds, int gw, int NGW, int wave, int lane) {
;     ...
;         r -= I_POOL;
;         if (r < I_QKV) {
;             const int j = r / 1536, q = r % 1536, kb = q / 96, nb = q % 96, n0 = 32 * nb;
;             const float* W = p.wqkv + (size_t)j * D * 3 * D; const float* gk = p.mix_norm + (size_t)(2 * j + 1) * D;
;             if (n0 < 2048) { const int pn = n0 >> 8, nl = n0 & 255, wc = nl >> 6, dd = nl & 63, bj = dd >> 5;
;                 transpose_item(W, 3 * D, 64 * kb, n0, gk, (bf16_t*)(p.ws + WS_WQK) + (size_t)j * 2048 * D, D, 256 * pn + 128 * bj + 32 * wc, scr, lane); }
;             else transpose_item(W, 3 * D, 64 * kb, n0, gk, (bf16_t*)(p.ws + WS_WVT) + (size_t)j * D * D, D, n0 - 2048, scr, lane);
.LBB0_47:
	s_andn2_b64 vcc, exec, s[6:7]
	s_cbranch_vccnz .LBB0_53
	s_add_i32 s0, s3, 0xffffff00
	s_cmpk_gt_u32 s0, 0x5ff
	s_cselect_b64 s[14:15], -1, 0
	s_add_i32 s6, s3, 0xfffff900
	s_cmpk_lt_u32 s0, 0x600
	s_cselect_b32 s0, s0, s6
	s_mul_hi_u32 s16, s0, 0xaaaaaaab
	s_lshr_b32 s6, s16, 6
	s_mulk_i32 s6, 0x60
	s_sub_i32 s81, s0, s6
	s_lshl_b32 s0, s81, 5
	s_and_b64 s[6:7], s[14:15], exec
	s_cselect_b32 s6, 0xc00000, 0
	s_add_u32 s79, s92, s6
	s_addc_u32 s80, s93, 0
	s_and_b64 s[6:7], s[14:15], exec
	s_cselect_b32 s6, s78, 0x1000
	s_add_u32 s12, s82, s6
	s_addc_u32 s13, s83, 0
	s_and_b32 s6, s16, 0xffffffc0
	v_or_b32_e32 v8, s6, v1
	v_add_u32_e32 v14, v24, v31
	v_add_u32_e32 v12, v24, v32
	s_cmp_gt_u32 s81, 63
	s_mov_b64 s[16:17], -1
	v_add_u32_e32 v6, s6, v1
	v_or_b32_e32 v76, 2, v8
	v_or_b32_e32 v75, 4, v8
	v_or_b32_e32 v74, 6, v8
	v_or_b32_e32 v73, 8, v8
	v_or_b32_e32 v72, 10, v8
	v_or_b32_e32 v71, 12, v8
	v_or_b32_e32 v70, 14, v8
	v_or_b32_e32 v69, 16, v8
	v_or_b32_e32 v68, 18, v8
	v_or_b32_e32 v67, 20, v8
	v_or_b32_e32 v66, 22, v8
	v_or_b32_e32 v65, 24, v8
	v_or_b32_e32 v64, 26, v8
	v_or_b32_e32 v62, 28, v8
	v_or_b32_e32 v63, 30, v8
	v_or_b32_e32 v54, 32, v8
	v_or_b32_e32 v55, 34, v8
	v_or_b32_e32 v56, 36, v8
	v_or_b32_e32 v57, 38, v8
	v_or_b32_e32 v58, 40, v8
	v_or_b32_e32 v59, 42, v8
	v_or_b32_e32 v60, 44, v8
	v_or_b32_e32 v61, 46, v8
	v_or_b32_e32 v52, 48, v8
	v_or_b32_e32 v53, 50, v8
	v_or_b32_e32 v51, 52, v8
	v_or_b32_e32 v23, 54, v8
	v_or_b32_e32 v22, 56, v8
	v_or_b32_e32 v21, 58, v8
	v_or_b32_e32 v20, 60, v8
	v_or_b32_e32 v19, 62, v8
	v_add_u32_e32 v18, 0x400, v14
	v_add_u32_e32 v17, 0x400, v49
	v_add_u32_e32 v16, 0x400, v50
	v_add_u32_e32 v15, 0x400, v12
	v_add_u32_e32 v13, 0x800, v12
	s_cbranch_scc0 .LBB0_50
	s_and_b64 s[16:17], s[14:15], exec
	s_cselect_b32 s7, 0x200000, 0
	s_add_u32 s17, s31, s7
	s_addc_u32 s82, s34, 0
	s_add_i32 s16, s0, 0xfffff800
	s_lshl_b64 s[84:85], s[0:1], 2
	s_add_u32 s84, s79, s84
	s_addc_u32 s85, s80, s85
	v_lshl_add_u64 v[10:11], s[84:85], 0, v[2:3]
	v_mad_u64_u32 v[78:79], s[84:85], v8, s78, v[10:11]
	global_load_dword v5, v[78:79], off
	v_mad_u64_u32 v[78:79], s[84:85], v76, s78, v[10:11]
	global_load_dword v77, v[78:79], off
	v_mad_u64_u32 v[78:79], s[84:85], v75, s78, v[10:11]
	global_load_dword v82, v[78:79], off
	v_mad_u64_u32 v[78:79], s[84:85], v74, s78, v[10:11]
	global_load_dword v83, v[78:79], off
	v_mad_u64_u32 v[78:79], s[84:85], v73, s78, v[10:11]
	global_load_dword v84, v[78:79], off
	v_mad_u64_u32 v[78:79], s[84:85], v72, s78, v[10:11]
	global_load_dword v85, v[78:79], off
	v_mad_u64_u32 v[78:79], s[84:85], v71, s78, v[10:11]
	global_load_dword v86, v[78:79], off
	v_mad_u64_u32 v[78:79], s[84:85], v70, s78, v[10:11]
	global_load_dword v87, v[78:79], off
	v_mad_u64_u32 v[78:79], s[84:85], v69, s78, v[10:11]
	global_load_dword v88, v[78:79], off
	v_mad_u64_u32 v[78:79], s[84:85], v68, s78, v[10:11]
	global_load_dword v89, v[78:79], off
	v_mad_u64_u32 v[78:79], s[84:85], v67, s78, v[10:11]
	global_load_dword v90, v[78:79], off
	v_mad_u64_u32 v[78:79], s[84:85], v66, s78, v[10:11]
	global_load_dword v91, v[78:79], off
	v_mad_u64_u32 v[78:79], s[84:85], v65, s78, v[10:11]
	global_load_dword v92, v[78:79], off
	v_mad_u64_u32 v[78:79], s[84:85], v64, s78, v[10:11]
	global_load_dword v93, v[78:79], off
	v_mad_u64_u32 v[78:79], s[84:85], v62, s78, v[10:11]
	global_load_dword v94, v[78:79], off
	v_mad_u64_u32 v[78:79], s[84:85], v63, s78, v[10:11]
	global_load_dword v95, v[78:79], off
	v_mad_u64_u32 v[78:79], s[84:85], v54, s78, v[10:11]
	global_load_dword v96, v[78:79], off
	v_mad_u64_u32 v[78:79], s[84:85], v55, s78, v[10:11]
	global_load_dword v97, v[78:79], off
	v_mad_u64_u32 v[78:79], s[84:85], v56, s78, v[10:11]
	global_load_dword v98, v[78:79], off
	v_mad_u64_u32 v[78:79], s[84:85], v57, s78, v[10:11]
	global_load_dword v99, v[78:79], off
	v_mad_u64_u32 v[78:79], s[84:85], v58, s78, v[10:11]
	global_load_dword v100, v[78:79], off
	v_mad_u64_u32 v[78:79], s[84:85], v59, s78, v[10:11]
	global_load_dword v101, v[78:79], off
	v_mad_u64_u32 v[78:79], s[84:85], v60, s78, v[10:11]
	global_load_dword v102, v[78:79], off
	v_mad_u64_u32 v[78:79], s[84:85], v61, s78, v[10:11]
	global_load_dword v103, v[78:79], off
	v_mad_u64_u32 v[78:79], s[84:85], v52, s78, v[10:11]
	global_load_dword v104, v[78:79], off
	v_mad_u64_u32 v[78:79], s[84:85], v53, s78, v[10:11]
	v_mov_b32_e32 v9, v3
	global_load_dword v105, v[78:79], off
	v_mad_u64_u32 v[78:79], s[84:85], v51, s78, v[10:11]
	global_load_dword v106, v[78:79], off
	v_lshl_add_u64 v[78:79], v[8:9], 2, s[12:13]
	global_load_dword v9, v[78:79], off
	v_mov_b32_e32 v7, v3
	v_lshl_add_u64 v[78:79], v[6:7], 2, s[12:13]
	global_load_dword v7, v[78:79], off offset:8
	global_load_dword v107, v[78:79], off offset:16
	global_load_dword v108, v[78:79], off offset:24
	global_load_dword v109, v[78:79], off offset:32
	v_mad_u64_u32 v[80:81], s[84:85], v23, s78, v[10:11]
	global_load_dword v110, v[78:79], off offset:40
	global_load_dword v111, v[78:79], off offset:48
	global_load_dword v112, v[80:81], off
	global_load_dword v113, v[78:79], off offset:56
	global_load_dword v114, v[78:79], off offset:64
	global_load_dword v115, v[78:79], off offset:72
	global_load_dword v116, v[78:79], off offset:80
	v_mad_u64_u32 v[80:81], s[84:85], v22, s78, v[10:11]
	global_load_dword v117, v[78:79], off offset:88
	global_load_dword v118, v[78:79], off offset:96
	global_load_dword v119, v[80:81], off
	global_load_dword v120, v[78:79], off offset:104
	global_load_dword v121, v[78:79], off offset:112
	global_load_dword v122, v[78:79], off offset:120
	global_load_dword v123, v[78:79], off offset:128
	v_mad_u64_u32 v[80:81], s[84:85], v21, s78, v[10:11]
	global_load_dword v124, v[78:79], off offset:136
	global_load_dword v125, v[78:79], off offset:144
	global_load_dword v126, v[80:81], off
	global_load_dword v127, v[78:79], off offset:152
	global_load_dword v128, v[78:79], off offset:160
	global_load_dword v129, v[78:79], off offset:168
	global_load_dword v130, v[78:79], off offset:176
	v_mad_u64_u32 v[80:81], s[84:85], v20, s78, v[10:11]
	global_load_dword v131, v[78:79], off offset:184
	global_load_dword v132, v[78:79], off offset:192
	s_nop 0
	global_load_dword v80, v[80:81], off
	s_nop 0
	global_load_dword v81, v[78:79], off offset:200
	global_load_dword v133, v[78:79], off offset:208
	global_load_dword v134, v[78:79], off offset:216
	global_load_dword v135, v[78:79], off offset:224
	v_mad_u64_u32 v[10:11], s[84:85], v19, s78, v[10:11]
	global_load_dword v136, v[78:79], off offset:232
	global_load_dword v137, v[78:79], off offset:240
	s_nop 0
	global_load_dword v10, v[10:11], off
	s_nop 0
	global_load_dword v11, v[78:79], off offset:248
	s_mov_b32 s7, s1
	s_lshl_b64 s[84:85], s[6:7], 1
	s_add_u32 s84, s17, s84
	s_addc_u32 s85, s82, s85
	s_waitcnt vmcnt(36)
; #define LAS __attribute__((address_space(3)))
; __device__ __forceinline__ unsigned cvt_pk_bf16(float lo, float hi) { const f32x2 v = {lo, hi}; const bf16x2_t b = __builtin_convertvector(v, bf16x2_t); return __builtin_bit_cast(unsigned, b); }
; __device__ __forceinline__ void transpose_item(const float* W, int ldn, int k0, int n0, const float* gk, bf16_t* WT, int ldk, int drow0, LAS float* scr, int lane, const float* gn = nullptr) {
;     ...
;     for (int i = 0; i < 32; ++i) { const int kk = 2 * i + (lane >> 5); float v = wv[i] * gnv; if (gk) v *= gk[k0 + kk]; scr[kk * 33 + (lane & 31)] = v; }
;     asm volatile("s_waitcnt lgkmcnt(0)" ::: "memory");
;     const int c = lane & 7;
; #pragma unroll
;     for (int j = 0; j < 4; ++j) { const int n = (lane >> 3) + 8 * j; const LAS float* s = scr + (8 * c) * 33 + n;
;         u32x4 o; o.x = cvt_pk_bf16(s[0 * 33], s[1 * 33]); o.y = cvt_pk_bf16(s[2 * 33], s[3 * 33]); o.z = cvt_pk_bf16(s[4 * 33], s[5 * 33]); o.w = cvt_pk_bf16(s[6 * 33], s[7 * 33]);
;         *(u32x4*)(WT + (size_t)(drow0 + n) * ldk + k0 + 8 * c) = o; }
;     asm volatile("s_waitcnt lgkmcnt(0)" ::: "memory");
	v_mul_f32_e32 v5, v5, v9
	ds_write_b32 v25, v5
	s_waitcnt vmcnt(35)
	v_mul_f32_e32 v5, v77, v7
	s_waitcnt vmcnt(34)
	v_mul_f32_e32 v7, v82, v107
	ds_write2_b32 v14, v5, v7 offset1:66
	s_waitcnt vmcnt(33)
	v_mul_f32_e32 v5, v83, v108
	s_waitcnt vmcnt(32)
	v_mul_f32_e32 v7, v84, v109
	ds_write2_b32 v14, v5, v7 offset0:132 offset1:198
	s_waitcnt vmcnt(31)
	v_mul_f32_e32 v5, v85, v110
	s_waitcnt vmcnt(30)
	v_mul_f32_e32 v7, v86, v111
	ds_write2_b32 v18, v5, v7 offset0:8 offset1:74
	s_waitcnt vmcnt(28)
	v_mul_f32_e32 v5, v87, v113
	s_waitcnt vmcnt(27)
	v_mul_f32_e32 v7, v88, v114
	ds_write2_b32 v49, v5, v7 offset1:66
	s_waitcnt vmcnt(26)
	v_mul_f32_e32 v5, v89, v115
	s_waitcnt vmcnt(25)
	v_mul_f32_e32 v7, v90, v116
	ds_write2_b32 v49, v5, v7 offset0:132 offset1:198
	s_waitcnt vmcnt(24)
	v_mul_f32_e32 v5, v91, v117
	s_waitcnt vmcnt(23)
	v_mul_f32_e32 v7, v92, v118
	ds_write2_b32 v17, v5, v7 offset0:8 offset1:74
	s_waitcnt vmcnt(21)
	v_mul_f32_e32 v5, v93, v120
	s_waitcnt vmcnt(20)
	v_mul_f32_e32 v7, v94, v121
	ds_write2_b32 v50, v5, v7 offset1:66
	s_waitcnt vmcnt(19)
	v_mul_f32_e32 v5, v95, v122
	s_waitcnt vmcnt(18)
	v_mul_f32_e32 v7, v96, v123
	ds_write2_b32 v50, v5, v7 offset0:132 offset1:198
	s_waitcnt vmcnt(17)
	v_mul_f32_e32 v5, v97, v124
	s_waitcnt vmcnt(16)
	v_mul_f32_e32 v7, v98, v125
	ds_write2_b32 v16, v5, v7 offset0:8 offset1:74
	s_waitcnt vmcnt(14)
	v_mul_f32_e32 v5, v99, v127
	s_waitcnt vmcnt(13)
	v_mul_f32_e32 v7, v100, v128
	ds_write2_b32 v12, v5, v7 offset1:66
	s_waitcnt vmcnt(12)
	v_mul_f32_e32 v5, v101, v129
	s_waitcnt vmcnt(11)
	v_mul_f32_e32 v7, v102, v130
	ds_write2_b32 v12, v5, v7 offset0:132 offset1:198
	s_waitcnt vmcnt(10)
	v_mul_f32_e32 v5, v103, v131
	s_waitcnt vmcnt(9)
	v_mul_f32_e32 v7, v104, v132
	ds_write2_b32 v15, v5, v7 offset0:8 offset1:74
	s_waitcnt vmcnt(7)
	v_mul_f32_e32 v5, v105, v81
	s_waitcnt vmcnt(6)
	v_mul_f32_e32 v7, v106, v133
	ds_write2_b32 v15, v5, v7 offset0:140 offset1:206
	s_waitcnt vmcnt(5)
	v_mul_f32_e32 v5, v112, v134
	s_waitcnt vmcnt(4)
	v_mul_f32_e32 v7, v119, v135
	ds_write2_b32 v13, v5, v7 offset0:16 offset1:82
	s_waitcnt vmcnt(3)
	v_mul_f32_e32 v5, v126, v136
	s_waitcnt vmcnt(2)
	v_mul_f32_e32 v7, v80, v137
	ds_write2_b32 v13, v5, v7 offset0:148 offset1:214
	s_waitcnt vmcnt(0)
	v_mul_f32_e32 v5, v10, v11
	ds_write_b32 v12, v5 offset:3168
	s_waitcnt lgkmcnt(0)
	ds_read2_b32 v[10:11], v27 offset0:33 offset1:41
	ds_read2_b32 v[82:83], v27 offset1:8
	ds_read2_b32 v[84:85], v27 offset0:66 offset1:74
	ds_read2_b32 v[86:87], v27 offset0:99 offset1:107
	ds_read2_b32 v[88:89], v27 offset0:132 offset1:140
	ds_read2_b32 v[90:91], v27 offset0:165 offset1:173
	ds_read2_b32 v[92:93], v27 offset0:198 offset1:206
	ds_read2_b32 v[94:95], v27 offset0:231 offset1:239
	v_or_b32_e32 v98, s16, v26
	v_mov_b32_e32 v5, v3
	v_ashrrev_i32_e32 v99, 31, v98
	v_lshl_add_u64 v[96:97], s[84:85], 0, v[4:5]
	v_lshlrev_b64 v[98:99], 11, v[98:99]
	s_waitcnt lgkmcnt(6)
	v_cvt_pk_bf16_f32 v78, v82, v10
	s_waitcnt lgkmcnt(4)
	v_cvt_pk_bf16_f32 v79, v84, v86
	s_waitcnt lgkmcnt(2)
	v_cvt_pk_bf16_f32 v80, v88, v90
	s_waitcnt lgkmcnt(0)
	v_cvt_pk_bf16_f32 v81, v92, v94
	v_lshl_add_u64 v[98:99], v[96:97], 0, v[98:99]
	v_or_b32_e32 v10, s16, v28
	global_store_dwordx4 v[98:99], v[78:81], off nt
	s_nop 1
	v_cvt_pk_bf16_f32 v78, v83, v11
	v_ashrrev_i32_e32 v11, 31, v10
	v_cvt_pk_bf16_f32 v79, v85, v87
	v_cvt_pk_bf16_f32 v80, v89, v91
	v_cvt_pk_bf16_f32 v81, v93, v95
	v_lshlrev_b64 v[10:11], 11, v[10:11]
	ds_read2_b32 v[82:83], v27 offset0:49 offset1:57
	ds_read2_b32 v[84:85], v27 offset0:16 offset1:24
	ds_read2_b32 v[86:87], v27 offset0:82 offset1:90
	ds_read2_b32 v[88:89], v27 offset0:115 offset1:123
	ds_read2_b32 v[90:91], v27 offset0:148 offset1:156
	ds_read2_b32 v[92:93], v27 offset0:181 offset1:189
	ds_read2_b32 v[94:95], v27 offset0:214 offset1:222
	ds_read2_b32 v[98:99], v27 offset0:247 offset1:255
	v_lshl_add_u64 v[10:11], v[96:97], 0, v[10:11]
	global_store_dwordx4 v[10:11], v[78:81], off nt
	v_or_b32_e32 v10, s16, v29
	v_ashrrev_i32_e32 v11, 31, v10
	v_lshlrev_b64 v[10:11], 11, v[10:11]
	s_waitcnt lgkmcnt(6)
	v_cvt_pk_bf16_f32 v78, v84, v82
	s_waitcnt lgkmcnt(4)
	v_cvt_pk_bf16_f32 v79, v86, v88
	s_waitcnt lgkmcnt(2)
	v_cvt_pk_bf16_f32 v80, v90, v92
	s_waitcnt lgkmcnt(0)
	v_cvt_pk_bf16_f32 v81, v94, v98
	v_lshl_add_u64 v[10:11], v[96:97], 0, v[10:11]
	global_store_dwordx4 v[10:11], v[78:81], off nt
	v_or_b32_e32 v10, s16, v30
	v_ashrrev_i32_e32 v11, 31, v10
	v_lshlrev_b64 v[10:11], 11, v[10:11]
	v_cvt_pk_bf16_f32 v78, v85, v83
	v_cvt_pk_bf16_f32 v79, v87, v89
	v_cvt_pk_bf16_f32 v80, v91, v93
	v_cvt_pk_bf16_f32 v81, v95, v99
	v_lshl_add_u64 v[10:11], v[96:97], 0, v[10:11]
	global_store_dwordx4 v[10:11], v[78:81], off nt
	s_waitcnt lgkmcnt(0)
	s_mov_b64 s[16:17], 0
; #define LAS __attribute__((address_space(3)))
; __device__ __forceinline__ void transpose_item(const float* W, int ldn, int k0, int n0, const float* gk, bf16_t* WT, int ldk, int drow0, LAS float* scr, int lane, const float* gn = nullptr) {
;     const float gnv = gn ? gn[lane & 31] : 1.f;
;     float wv[32];
; #pragma unroll
;     for (int i = 0; i < 32; ++i) wv[i] = W[(size_t)(k0 + 2 * i + (lane >> 5)) * ldn + n0 + (lane & 31)];
; __device__ __forceinline__ void convert_weights(const Params& p, LAS unsigned char* lds, int gw, int NGW, int wave, int lane) {
;     ...
;             if (n0 < 2048) { const int pn = n0 >> 8, nl = n0 & 255, wc = nl >> 6, dd = nl & 63, bj = dd >> 5;
;                 transpose_item(W, 3 * D, 64 * kb, n0, gk, (bf16_t*)(p.ws + WS_WQK) + (size_t)j * 2048 * D, D, 256 * pn + 128 * bj + 32 * wc, scr, lane); }
.LBB0_50:
	s_andn2_b64 vcc, exec, s[16:17]
	s_cbranch_vccnz .LBB0_52
	s_and_b64 s[14:15], s[14:15], exec
	s_cselect_b32 s7, 0x400000, 0
	s_add_u32 s15, s35, s7
	s_addc_u32 s16, s38, 0
	s_lshl_b32 s14, s81, 7
	s_and_b32 s7, s0, 0x700
	s_and_b32 s14, s14, 0x80
	s_or_b32 s7, s7, s14
	s_lshl_b32 s14, s81, 4
	s_and_b32 s14, s14, 0x60
	s_or_b32 s14, s7, s14
	s_lshl_b64 s[82:83], s[0:1], 2
	s_add_u32 s82, s79, s82
	s_addc_u32 s83, s80, s83
	v_lshl_add_u64 v[10:11], s[82:83], 0, v[2:3]
	v_mov_b32_e32 v9, v3
	v_mad_u64_u32 v[78:79], s[80:81], v8, s78, v[10:11]
	v_mad_u64_u32 v[76:77], s[80:81], v76, s78, v[10:11]
	v_mad_u64_u32 v[80:81], s[80:81], v75, s78, v[10:11]
	v_mad_u64_u32 v[74:75], s[80:81], v74, s78, v[10:11]
	v_mad_u64_u32 v[82:83], s[80:81], v73, s78, v[10:11]
	v_mad_u64_u32 v[72:73], s[80:81], v72, s78, v[10:11]
	v_mad_u64_u32 v[84:85], s[80:81], v71, s78, v[10:11]
	v_mad_u64_u32 v[70:71], s[80:81], v70, s78, v[10:11]
	v_lshl_add_u64 v[8:9], v[8:9], 2, s[12:13]
	v_mov_b32_e32 v7, v3
	global_load_dword v5, v[78:79], off
	s_nop 0
	global_load_dword v76, v[76:77], off
	s_nop 0
	global_load_dword v77, v[80:81], off
	global_load_dword v78, v[74:75], off
	global_load_dword v79, v[82:83], off
	s_nop 0
	global_load_dword v80, v[72:73], off
	global_load_dword v81, v[84:85], off
	global_load_dword v82, v[70:71], off
	v_mad_u64_u32 v[70:71], s[80:81], v69, s78, v[10:11]
	v_mad_u64_u32 v[68:69], s[80:81], v68, s78, v[10:11]
	v_mad_u64_u32 v[72:73], s[80:81], v67, s78, v[10:11]
	v_mad_u64_u32 v[66:67], s[80:81], v66, s78, v[10:11]
	v_mad_u64_u32 v[74:75], s[80:81], v65, s78, v[10:11]
	v_mad_u64_u32 v[64:65], s[80:81], v64, s78, v[10:11]
	global_load_dword v83, v[8:9], off
	v_mad_u64_u32 v[8:9], s[80:81], v62, s78, v[10:11]
	v_mad_u64_u32 v[62:63], s[80:81], v63, s78, v[10:11]
	v_lshl_add_u64 v[6:7], v[6:7], 2, s[12:13]
	global_load_dword v84, v[6:7], off offset:8
	global_load_dword v85, v[6:7], off offset:16
	s_nop 0
	global_load_dword v70, v[70:71], off
	s_nop 0
	global_load_dword v68, v[68:69], off
	s_nop 0
	global_load_dword v69, v[72:73], off
	global_load_dword v71, v[66:67], off
	s_nop 0
	global_load_dword v72, v[74:75], off
	global_load_dword v73, v[64:65], off
	s_nop 0
	global_load_dword v74, v[8:9], off
	global_load_dword v75, v[62:63], off
	v_mad_u64_u32 v[8:9], s[12:13], v54, s78, v[10:11]
	v_mad_u64_u32 v[62:63], s[12:13], v56, s78, v[10:11]
	v_mad_u64_u32 v[56:57], s[12:13], v57, s78, v[10:11]
	v_mad_u64_u32 v[64:65], s[12:13], v58, s78, v[10:11]
	v_mad_u64_u32 v[58:59], s[12:13], v59, s78, v[10:11]
	v_mad_u64_u32 v[66:67], s[12:13], v60, s78, v[10:11]
	v_mad_u64_u32 v[60:61], s[12:13], v61, s78, v[10:11]
	v_mad_u64_u32 v[54:55], s[12:13], v55, s78, v[10:11]
	global_load_dword v86, v[8:9], off
	global_load_dword v87, v[54:55], off
	s_nop 0
	global_load_dword v62, v[62:63], off
	s_nop 0
	global_load_dword v56, v[56:57], off
	s_nop 0
	global_load_dword v57, v[64:65], off
	s_nop 0
	global_load_dword v58, v[58:59], off
	s_nop 0
	global_load_dword v59, v[66:67], off
	s_nop 0
	global_load_dword v60, v[60:61], off
	v_mad_u64_u32 v[8:9], s[12:13], v52, s78, v[10:11]
	v_mad_u64_u32 v[52:53], s[12:13], v53, s78, v[10:11]
	global_load_dword v61, v[8:9], off
	global_load_dword v63, v[52:53], off
	v_mad_u64_u32 v[8:9], s[12:13], v51, s78, v[10:11]
	global_load_dword v51, v[6:7], off offset:24
	global_load_dword v64, v[6:7], off offset:32
	global_load_dword v65, v[6:7], off offset:40
	global_load_dword v66, v[6:7], off offset:48
	global_load_dword v67, v[6:7], off offset:56
	global_load_dword v88, v[6:7], off offset:64
	global_load_dword v89, v[6:7], off offset:72
	global_load_dword v90, v[6:7], off offset:80
	global_load_dword v91, v[6:7], off offset:88
	global_load_dword v92, v[6:7], off offset:96
	global_load_dword v93, v[6:7], off offset:104
	global_load_dword v94, v[6:7], off offset:112
	global_load_dword v95, v[6:7], off offset:120
	global_load_dword v96, v[6:7], off offset:128
	global_load_dword v97, v[6:7], off offset:136
	global_load_dword v98, v[6:7], off offset:144
	v_mad_u64_u32 v[52:53], s[12:13], v23, s78, v[10:11]
	v_mad_u64_u32 v[22:23], s[12:13], v22, s78, v[10:11]
	v_mad_u64_u32 v[54:55], s[12:13], v21, s78, v[10:11]
	v_mad_u64_u32 v[20:21], s[12:13], v20, s78, v[10:11]
	v_mad_u64_u32 v[10:11], s[12:13], v19, s78, v[10:11]
	global_load_dword v19, v[6:7], off offset:152
	global_load_dword v99, v[6:7], off offset:160
	s_nop 0
	global_load_dword v8, v[8:9], off
	s_nop 0
	global_load_dword v9, v[6:7], off offset:168
	global_load_dword v100, v[6:7], off offset:176
	s_nop 0
	global_load_dword v52, v[52:53], off
	s_nop 0
	global_load_dword v53, v[6:7], off offset:184
	global_load_dword v101, v[6:7], off offset:192
	s_nop 0
	global_load_dword v22, v[22:23], off
	s_nop 0
	global_load_dword v23, v[6:7], off offset:200
	global_load_dword v102, v[6:7], off offset:208
	s_nop 0
	global_load_dword v54, v[54:55], off
	s_nop 0
	global_load_dword v55, v[6:7], off offset:216
	global_load_dword v103, v[6:7], off offset:224
	s_nop 0
	global_load_dword v20, v[20:21], off
	s_nop 0
	global_load_dword v21, v[6:7], off offset:232
	global_load_dword v104, v[6:7], off offset:240
	s_nop 0
	global_load_dword v10, v[10:11], off
	s_nop 0
	global_load_dword v6, v[6:7], off offset:248
	s_mov_b32 s7, s1
	s_lshl_b64 s[6:7], s[6:7], 1
	s_add_u32 s6, s15, s6
	s_addc_u32 s7, s16, s7
	s_waitcnt vmcnt(53)
; #define LAS __attribute__((address_space(3)))
; __device__ __forceinline__ unsigned cvt_pk_bf16(float lo, float hi) { const f32x2 v = {lo, hi}; const bf16x2_t b = __builtin_convertvector(v, bf16x2_t); return __builtin_bit_cast(unsigned, b); }
; __device__ __forceinline__ void transpose_item(const float* W, int ldn, int k0, int n0, const float* gk, bf16_t* WT, int ldk, int drow0, LAS float* scr, int lane, const float* gn = nullptr) {
;     ...
;     for (int i = 0; i < 32; ++i) { const int kk = 2 * i + (lane >> 5); float v = wv[i] * gnv; if (gk) v *= gk[k0 + kk]; scr[kk * 33 + (lane & 31)] = v; }
;     asm volatile("s_waitcnt lgkmcnt(0)" ::: "memory");
;     const int c = lane & 7;
; #pragma unroll
;     for (int j = 0; j < 4; ++j) { const int n = (lane >> 3) + 8 * j; const LAS float* s = scr + (8 * c) * 33 + n;
;         u32x4 o; o.x = cvt_pk_bf16(s[0 * 33], s[1 * 33]); o.y = cvt_pk_bf16(s[2 * 33], s[3 * 33]); o.z = cvt_pk_bf16(s[4 * 33], s[5 * 33]); o.w = cvt_pk_bf16(s[6 * 33], s[7 * 33]);
;         *(u32x4*)(WT + (size_t)(drow0 + n) * ldk + k0 + 8 * c) = o; }
;     asm volatile("s_waitcnt lgkmcnt(0)" ::: "memory");
	v_mul_f32_e32 v7, v77, v85
	v_mul_f32_e32 v5, v5, v83
	ds_write_b32 v25, v5
	v_mul_f32_e32 v5, v76, v84
	ds_write2_b32 v14, v5, v7 offset1:66
	s_waitcnt vmcnt(33)
	v_mul_f32_e32 v7, v79, v64
	v_mul_f32_e32 v5, v78, v51
	ds_write2_b32 v14, v5, v7 offset0:132 offset1:198
	s_waitcnt vmcnt(32)
	v_mul_f32_e32 v5, v80, v65
	s_waitcnt vmcnt(31)
	v_mul_f32_e32 v7, v81, v66
	ds_write2_b32 v18, v5, v7 offset0:8 offset1:74
	s_waitcnt vmcnt(30)
	v_mul_f32_e32 v5, v82, v67
	s_waitcnt vmcnt(29)
	v_mul_f32_e32 v7, v70, v88
	ds_write2_b32 v49, v5, v7 offset1:66
	s_waitcnt vmcnt(28)
	v_mul_f32_e32 v5, v68, v89
	s_waitcnt vmcnt(27)
	v_mul_f32_e32 v7, v69, v90
	ds_write2_b32 v49, v5, v7 offset0:132 offset1:198
	s_waitcnt vmcnt(26)
	v_mul_f32_e32 v5, v71, v91
	s_waitcnt vmcnt(25)
	v_mul_f32_e32 v7, v72, v92
	ds_write2_b32 v17, v5, v7 offset0:8 offset1:74
	s_waitcnt vmcnt(24)
	v_mul_f32_e32 v5, v73, v93
	s_waitcnt vmcnt(23)
	v_mul_f32_e32 v7, v74, v94
	ds_write2_b32 v50, v5, v7 offset1:66
	s_waitcnt vmcnt(22)
	v_mul_f32_e32 v5, v75, v95
	s_waitcnt vmcnt(21)
	v_mul_f32_e32 v7, v86, v96
	ds_write2_b32 v50, v5, v7 offset0:132 offset1:198
	s_waitcnt vmcnt(20)
	v_mul_f32_e32 v5, v87, v97
	s_waitcnt vmcnt(19)
	v_mul_f32_e32 v7, v62, v98
	ds_write2_b32 v16, v5, v7 offset0:8 offset1:74
	s_waitcnt vmcnt(18)
	v_mul_f32_e32 v5, v56, v19
	s_waitcnt vmcnt(17)
	v_mul_f32_e32 v7, v57, v99
	ds_write2_b32 v12, v5, v7 offset1:66
	s_waitcnt vmcnt(15)
	v_mul_f32_e32 v5, v58, v9
	s_waitcnt vmcnt(14)
	v_mul_f32_e32 v7, v59, v100
	ds_write2_b32 v12, v5, v7 offset0:132 offset1:198
	s_waitcnt vmcnt(12)
	v_mul_f32_e32 v5, v60, v53
	s_waitcnt vmcnt(11)
	v_mul_f32_e32 v7, v61, v101
	ds_write2_b32 v15, v5, v7 offset0:8 offset1:74
	s_waitcnt vmcnt(9)
	v_mul_f32_e32 v5, v63, v23
	s_waitcnt vmcnt(8)
	v_mul_f32_e32 v7, v8, v102
	ds_write2_b32 v15, v5, v7 offset0:140 offset1:206
	s_waitcnt vmcnt(6)
	v_mul_f32_e32 v5, v52, v55
	s_waitcnt vmcnt(5)
	v_mul_f32_e32 v7, v22, v103
	ds_write2_b32 v13, v5, v7 offset0:16 offset1:82
	s_waitcnt vmcnt(3)
	v_mul_f32_e32 v5, v54, v21
	s_waitcnt vmcnt(2)
	v_mul_f32_e32 v7, v20, v104
	ds_write2_b32 v13, v5, v7 offset0:148 offset1:214
	s_waitcnt vmcnt(0)
	v_mul_f32_e32 v5, v10, v6
	ds_write_b32 v12, v5 offset:3168
	s_waitcnt lgkmcnt(0)
	ds_read2_b32 v[10:11], v27 offset0:33 offset1:41
	ds_read2_b32 v[12:13], v27 offset1:8
	ds_read2_b32 v[14:15], v27 offset0:66 offset1:74
	ds_read2_b32 v[16:17], v27 offset0:99 offset1:107
	ds_read2_b32 v[18:19], v27 offset0:132 offset1:140
	ds_read2_b32 v[20:21], v27 offset0:165 offset1:173
	ds_read2_b32 v[22:23], v27 offset0:198 offset1:206
	ds_read2_b32 v[52:53], v27 offset0:231 offset1:239
	v_mov_b32_e32 v5, v3
	v_lshl_add_u64 v[54:55], s[6:7], 0, v[4:5]
	v_or_b32_e32 v5, s14, v26
	v_lshlrev_b32_e32 v56, 11, v5
	v_mov_b32_e32 v57, v3
	s_waitcnt lgkmcnt(6)
	v_cvt_pk_bf16_f32 v6, v12, v10
	s_waitcnt lgkmcnt(4)
	v_cvt_pk_bf16_f32 v7, v14, v16
	s_waitcnt lgkmcnt(2)
	v_cvt_pk_bf16_f32 v8, v18, v20
	s_waitcnt lgkmcnt(0)
	v_cvt_pk_bf16_f32 v9, v22, v52
	v_lshl_add_u64 v[56:57], v[54:55], 0, v[56:57]
	global_store_dwordx4 v[56:57], v[6:9], off nt
	v_or_b32_e32 v5, s14, v28
	v_lshlrev_b32_e32 v10, 11, v5
	v_cvt_pk_bf16_f32 v6, v13, v11
	v_cvt_pk_bf16_f32 v7, v15, v17
	v_cvt_pk_bf16_f32 v8, v19, v21
	v_cvt_pk_bf16_f32 v9, v23, v53
	ds_read2_b32 v[12:13], v27 offset0:49 offset1:57
	ds_read2_b32 v[14:15], v27 offset0:16 offset1:24
	ds_read2_b32 v[16:17], v27 offset0:82 offset1:90
	ds_read2_b32 v[18:19], v27 offset0:115 offset1:123
	ds_read2_b32 v[20:21], v27 offset0:148 offset1:156
	ds_read2_b32 v[22:23], v27 offset0:181 offset1:189
	ds_read2_b32 v[52:53], v27 offset0:214 offset1:222
	ds_read2_b32 v[56:57], v27 offset0:247 offset1:255
	v_mov_b32_e32 v11, v3
	v_lshl_add_u64 v[10:11], v[54:55], 0, v[10:11]
	v_or_b32_e32 v5, s14, v29
	global_store_dwordx4 v[10:11], v[6:9], off nt
	v_lshlrev_b32_e32 v10, 11, v5
	v_mov_b32_e32 v11, v3
	s_waitcnt lgkmcnt(6)
	v_cvt_pk_bf16_f32 v6, v14, v12
	s_waitcnt lgkmcnt(4)
	v_cvt_pk_bf16_f32 v7, v16, v18
	s_waitcnt lgkmcnt(2)
	v_cvt_pk_bf16_f32 v8, v20, v22
	s_waitcnt lgkmcnt(0)
	v_cvt_pk_bf16_f32 v9, v52, v56
	v_lshl_add_u64 v[10:11], v[54:55], 0, v[10:11]
	v_or_b32_e32 v5, s14, v30
	global_store_dwordx4 v[10:11], v[6:9], off nt
	v_lshlrev_b32_e32 v10, 11, v5
	v_mov_b32_e32 v11, v3
	v_cvt_pk_bf16_f32 v6, v15, v13
	v_cvt_pk_bf16_f32 v7, v17, v19
	v_cvt_pk_bf16_f32 v8, v21, v23
	v_cvt_pk_bf16_f32 v9, v53, v57
	v_lshl_add_u64 v[10:11], v[54:55], 0, v[10:11]
	global_store_dwordx4 v[10:11], v[6:9], off nt
	s_waitcnt lgkmcnt(0)

; __device__ __forceinline__ float bf_lo(unsigned w) { return __uint_as_float(w << 16); }
; __device__ __forceinline__ float bf_hi(unsigned w) { return __uint_as_float(w & 0xffff0000u); }
; template <bool IN_BF16> __device__ __forceinline__ void pool_prep(const void* xin_, const float* g, bf16_t* Y, LAS unsigned char* lds, int vcu, int G) {
;     ...
;             const int T0 = run * RUN + k * 16, ts0 = T0 & (SEQ - 1);
;             const int nrow = (k == 0) ? 31 : 16, rbase = (k == 0) ? T0 - 15 : T0;
;             {
;                 f32x4 v[4][4];
; #pragma unroll
;                 for (int q = 0; q < 4; ++q) {
;                     const int i = wave + 8 * q; const bool ok = (i < nrow) && (((rbase + i) & (SEQ - 1)) <= ts0 + 15) ;
;                     const size_t rowo = (size_t)((i < nrow && rbase + i >= 0 && !(ts0 == 0 && k == 0 && i < 15)) ? rbase + i : T0) * D;
;                     if (q < 2 || k == 0) {
;                         if (IN_BF16) { const u32x2* xr = (const u32x2*)(xinb + rowo) + lane;
; #pragma unroll
;                             for (int j = 0; j < 4; ++j) { const u32x2 wv = xr[64 * j]; v[q][j] = (f32x4){bf_lo(wv.x), bf_hi(wv.x), bf_lo(wv.y), bf_hi(wv.y)}; } }
;                         else { const f32x4* xr = (const f32x4*)(xin + rowo) + lane;
; #pragma unroll
;                             for (int j = 0; j < 4; ++j) v[q][j] = xr[64 * j]; }
;                     }
.LBB0_69:
	s_lshl_b32 s55, s51, 4
	s_add_i32 s55, s55, s47
	s_and_b32 s16, s55, 0x1ff0
	s_add_i32 s53, s55, -15
	s_cmp_eq_u32 s51, 0
	s_cselect_b64 s[34:35], -1, 0
	s_and_b64 s[0:1], s[34:35], exec
	s_cselect_b32 s40, 31, 16
	s_cselect_b32 s54, s53, s55
	s_or_b32 s0, s16, s51
	s_cmp_eq_u32 s0, 0
	s_cselect_b64 s[30:31], -1, 0
	v_cmp_le_i32_e64 s[0:1], s40, v1
	v_cmp_gt_i32_e64 s[22:23], s40, v1
	s_and_saveexec_b64 s[16:17], s[22:23]
	v_add_u32_e32 v34, s54, v1
	v_cmp_gt_i32_e32 vcc, 0, v34
	s_and_b64 s[18:19], s[8:9], s[30:31]
	s_or_b64 s[18:19], vcc, s[18:19]
	s_andn2_b64 s[0:1], s[0:1], exec
	s_and_b64 s[18:19], s[18:19], exec
	s_or_b64 s[0:1], s[0:1], s[18:19]
	s_or_b64 exec, exec, s[16:17]
	s_and_saveexec_b64 s[16:17], s[0:1]
	v_mov_b32_e32 v34, s55
	s_or_b64 exec, exec, s[16:17]
	v_ashrrev_i32_e32 v35, 31, v34
	v_lshlrev_b64 v[34:35], 12, v[34:35]
	v_lshl_add_u64 v[34:35], v[68:69], 0, v[34:35]
	global_load_dwordx4 v[62:65], v[34:35], off nt
	global_load_dwordx4 v[58:61], v[34:35], off offset:1024 nt
	global_load_dwordx4 v[54:57], v[34:35], off offset:2048 nt
	global_load_dwordx4 v[50:53], v[34:35], off offset:3072 nt
	v_cmp_le_i32_e64 s[0:1], s40, v80
	v_cmp_gt_i32_e64 s[20:21], s40, v80
	s_and_saveexec_b64 s[16:17], s[20:21]
	v_add_u32_e32 v34, s54, v80
	v_cmp_gt_i32_e32 vcc, 0, v34
	s_and_b64 s[18:19], s[10:11], s[30:31]
	s_or_b64 s[18:19], vcc, s[18:19]
	s_andn2_b64 s[0:1], s[0:1], exec
	s_and_b64 s[18:19], s[18:19], exec
	s_or_b64 s[0:1], s[0:1], s[18:19]
	s_or_b64 exec, exec, s[16:17]
	s_and_saveexec_b64 s[16:17], s[0:1]
	v_mov_b32_e32 v34, s55
	s_or_b64 exec, exec, s[16:17]
	v_ashrrev_i32_e32 v35, 31, v34
	v_lshlrev_b64 v[34:35], 12, v[34:35]
	v_lshl_add_u64 v[34:35], v[68:69], 0, v[34:35]
	global_load_dwordx4 v[46:49], v[34:35], off nt
	global_load_dwordx4 v[42:45], v[34:35], off offset:1024 nt
	global_load_dwordx4 v[38:41], v[34:35], off offset:2048 nt
	s_nop 0
	global_load_dwordx4 v[34:37], v[34:35], off offset:3072 nt
	v_cmp_le_i32_e64 s[0:1], s40, v81
	v_cmp_gt_i32_e64 s[18:19], s40, v81
	s_and_saveexec_b64 s[16:17], s[18:19]
	v_add_u32_e32 v74, s54, v81
	v_cmp_gt_i32_e32 vcc, 0, v74
	s_and_b64 s[38:39], s[12:13], s[30:31]
	s_or_b64 s[38:39], vcc, s[38:39]
	s_andn2_b64 s[0:1], s[0:1], exec
	s_and_b64 s[38:39], s[38:39], exec
	s_or_b64 s[0:1], s[0:1], s[38:39]
	s_or_b64 exec, exec, s[16:17]
	s_and_saveexec_b64 s[16:17], s[0:1]
	v_mov_b32_e32 v74, s55
	s_or_b64 exec, exec, s[16:17]
	v_cndmask_b32_e64 v67, 0, 1, s[34:35]
	v_cmp_ne_u32_e64 s[0:1], 1, v67
	s_andn2_b64 vcc, exec, s[34:35]
	s_cbranch_vccz .LBB0_89
	v_cmp_le_i32_e64 s[38:39], s40, v82
	v_cmp_gt_i32_e64 s[16:17], s40, v82
	s_and_saveexec_b64 s[40:41], s[16:17]
	s_cbranch_execz .LBB0_90

; #define LAS __attribute__((address_space(3)))
; template <bool IN_BF16> __device__ __forceinline__ void pool_prep(const void* xin_, const float* g, bf16_t* Y, LAS unsigned char* lds, int vcu, int G) {
;     ...
;                 for (int q = 0; q < 4; ++q) {
;                     const int i = wave + 8 * q;
;                     if (i < nrow && (q < 2 || k == 0)) {
;                         const int row = rbase + i;
;                         LAS f32x4* hrow = (LAS f32x4*)(hs + (row & 31) * 1024) + lane;
;                         float s = 0.f;
; #pragma unroll
;                         for (int j = 0; j < 4; ++j) s += (v[q][j][0] * v[q][j][0] + v[q][j][1] * v[q][j][1]) + (v[q][j][2] * v[q][j][2] + v[q][j][3] * v[q][j][3]);
;                         float rstd = rsqrtf(wave_sum(s) * (1.f / D) + EPS);
;                         if (ts0 == 0 && k == 0 && i < 15) rstd = 0.f;
; #pragma unroll
;                         for (int j = 0; j < 4; ++j) { const f32x4 gg = *((const f32x4*)g + lane + 64 * j); hrow[64 * j] = v[q][j] * rstd * gg; }
;                     }
.LBB0_86:
	s_waitcnt vmcnt(7)
	v_pk_mul_f32 v[74:75], v[64:65], v[64:65]
	v_pk_mul_f32 v[88:89], v[62:63], v[62:63]
	s_waitcnt vmcnt(4)
	v_mul_f32_e32 v87, v50, v50
	v_pk_mov_b32 v[90:91], v[88:89], v[74:75] op_sel:[1,0]
	v_mov_b32_e32 v89, v75
	v_pk_add_f32 v[74:75], v[90:91], v[88:89]
	v_pk_mul_f32 v[88:89], v[60:61], v[60:61]
	v_pk_mul_f32 v[90:91], v[58:59], v[58:59]
	v_pk_add_f32 v[74:75], v[74:75], v[74:75] op_sel:[0,1] op_sel_hi:[1,0]
	v_pk_mov_b32 v[92:93], v[90:91], v[88:89] op_sel:[1,0]
	v_mov_b32_e32 v91, v89
	v_pk_add_f32 v[88:89], v[92:93], v[90:91]
	v_mul_f32_e32 v90, v51, v51
	v_pk_add_f32 v[88:89], v[88:89], v[88:89] op_sel:[0,1] op_sel_hi:[1,0]
	v_mov_b32_e32 v75, v87
	v_mov_b32_e32 v89, v90
	v_pk_add_f32 v[74:75], v[74:75], v[88:89]
	v_mul_f32_e32 v88, v55, v55
	v_mul_f32_e32 v91, v52, v52
	v_pk_fma_f32 v[88:89], v[54:55], v[54:55], v[88:89] op_sel_hi:[1,1,0]
	v_mul_f32_e32 v90, v57, v57
	v_mul_f32_e32 v92, v53, v53
	v_mov_b32_e32 v89, v91
	v_pk_fma_f32 v[90:91], v[56:57], v[56:57], v[90:91] op_sel_hi:[1,1,0]
	global_load_dwordx4 v[96:99], v[70:71], off offset:2048 nt
	global_load_dwordx4 v[100:103], v[70:71], off offset:3072 nt
	v_mov_b32_e32 v91, v92
	v_pk_add_f32 v[88:89], v[88:89], v[90:91]
	global_load_dwordx4 v[92:95], v[70:71], off offset:1024 nt
	v_pk_add_f32 v[74:75], v[74:75], v[88:89]
	global_load_dwordx4 v[88:91], v[70:71], off nt
	v_add_f32_e32 v74, v74, v75
	v_and_b32_e32 v75, 64, v67
	v_add_u32_e32 v75, 64, v75
	v_xor_b32_e32 v87, 1, v67
	v_cmp_lt_i32_e32 vcc, v87, v75
	s_and_b64 s[22:23], s[8:9], s[30:31]
	s_nop 0
	v_cndmask_b32_e32 v87, v67, v87, vcc
	v_lshlrev_b32_e32 v87, 2, v87
	ds_bpermute_b32 v87, v87, v74
	s_waitcnt lgkmcnt(0)
	v_add_f32_e32 v74, v74, v87
	v_xor_b32_e32 v87, 2, v67
	v_cmp_lt_i32_e32 vcc, v87, v75
	s_nop 1
	v_cndmask_b32_e32 v87, v67, v87, vcc
	v_lshlrev_b32_e32 v87, 2, v87
	ds_bpermute_b32 v87, v87, v74
	s_waitcnt lgkmcnt(0)
	v_add_f32_e32 v74, v74, v87
	v_xor_b32_e32 v87, 4, v67
	v_cmp_lt_i32_e32 vcc, v87, v75
	s_nop 1
	v_cndmask_b32_e32 v87, v67, v87, vcc
	v_lshlrev_b32_e32 v87, 2, v87
	ds_bpermute_b32 v87, v87, v74
	s_waitcnt lgkmcnt(0)
	v_add_f32_e32 v74, v74, v87
	v_xor_b32_e32 v87, 8, v67
	v_cmp_lt_i32_e32 vcc, v87, v75
	s_nop 1
	v_cndmask_b32_e32 v87, v67, v87, vcc
	v_lshlrev_b32_e32 v87, 2, v87
	ds_bpermute_b32 v87, v87, v74
	s_waitcnt lgkmcnt(0)
	v_add_f32_e32 v74, v74, v87
	v_xor_b32_e32 v87, 16, v67
	v_cmp_lt_i32_e32 vcc, v87, v75
	s_nop 1
	v_cndmask_b32_e32 v87, v67, v87, vcc
	v_lshlrev_b32_e32 v87, 2, v87
	ds_bpermute_b32 v87, v87, v74
	s_waitcnt lgkmcnt(0)
	v_add_f32_e32 v74, v74, v87
	v_xor_b32_e32 v87, 32, v67
	v_cmp_lt_i32_e32 vcc, v87, v75
	s_nop 1
	v_cndmask_b32_e32 v75, v67, v87, vcc
	v_lshlrev_b32_e32 v75, 2, v75
	ds_bpermute_b32 v75, v75, v74
	s_waitcnt lgkmcnt(0)
	v_add_f32_e32 v74, v74, v75
	v_fmamk_f32 v74, v74, 0x3a800000, v85
	v_mul_f32_e32 v75, 0x4b800000, v74
	v_cmp_gt_f32_e32 vcc, s45, v74
	s_nop 1
	v_cndmask_b32_e32 v74, v74, v75, vcc
	v_rsq_f32_e32 v74, v74
	v_add_lshl_u32 v75, s54, v1, 12
	v_and_b32_e32 v75, 0x1f000, v75
	v_add_u32_e32 v75, v77, v75
	v_mul_f32_e32 v87, 0x45800000, v74
	v_cndmask_b32_e32 v74, v74, v87, vcc
	v_cndmask_b32_e64 v74, v74, 0, s[22:23]
	v_pk_mul_f32 v[62:63], v[62:63], v[74:75] op_sel_hi:[1,0]
	v_pk_mul_f32 v[64:65], v[64:65], v[74:75] op_sel_hi:[1,0]
	v_pk_mul_f32 v[58:59], v[58:59], v[74:75] op_sel_hi:[1,0]
	v_pk_mul_f32 v[60:61], v[60:61], v[74:75] op_sel_hi:[1,0]
	v_pk_mul_f32 v[54:55], v[54:55], v[74:75] op_sel_hi:[1,0]
	v_pk_mul_f32 v[56:57], v[56:57], v[74:75] op_sel_hi:[1,0]
	v_pk_mul_f32 v[50:51], v[50:51], v[74:75] op_sel_hi:[1,0]
	v_pk_mul_f32 v[52:53], v[52:53], v[74:75] op_sel_hi:[1,0]
	s_waitcnt vmcnt(0)
	v_pk_mul_f32 v[64:65], v[90:91], v[64:65]
	v_pk_mul_f32 v[62:63], v[88:89], v[62:63]
	v_pk_mul_f32 v[60:61], v[94:95], v[60:61]
	v_pk_mul_f32 v[58:59], v[92:93], v[58:59]
	v_pk_mul_f32 v[56:57], v[98:99], v[56:57]
	v_pk_mul_f32 v[54:55], v[96:97], v[54:55]
	v_pk_mul_f32 v[52:53], v[102:103], v[52:53]
	v_pk_mul_f32 v[50:51], v[100:101], v[50:51]
	ds_write_b128 v75, v[62:65]
	ds_write_b128 v75, v[58:61] offset:1024
	ds_write_b128 v75, v[54:57] offset:2048
	ds_write_b128 v75, v[50:53] offset:3072
	s_or_b64 exec, exec, s[0:1]
	s_and_saveexec_b64 s[0:1], s[20:21]
	s_cbranch_execnz .LBB0_94

; #define LAS __attribute__((address_space(3)))
; __device__ __forceinline__ float bf_lo(unsigned w) { return __uint_as_float(w << 16); }
; __device__ __forceinline__ float bf_hi(unsigned w) { return __uint_as_float(w & 0xffff0000u); }
; template <bool IN_BF16> __device__ __forceinline__ void pool_prep(const void* xin_, const float* g, bf16_t* Y, LAS unsigned char* lds, int vcu, int G) {
;     ...
;                 for (int q = 0; q < 4; ++q) {
;                     const int i = wave + 8 * q; const bool ok = (i < nrow) && (((rbase + i) & (SEQ - 1)) <= ts0 + 15) ;
;                     const size_t rowo = (size_t)((i < nrow && rbase + i >= 0 && !(ts0 == 0 && k == 0 && i < 15)) ? rbase + i : T0) * D;
;                     if (q < 2 || k == 0) {
;                         if (IN_BF16) { const u32x2* xr = (const u32x2*)(xinb + rowo) + lane;
; #pragma unroll
;                             for (int j = 0; j < 4; ++j) { const u32x2 wv = xr[64 * j]; v[q][j] = (f32x4){bf_lo(wv.x), bf_hi(wv.x), bf_lo(wv.y), bf_hi(wv.y)}; } }
;                         else { const f32x4* xr = (const f32x4*)(xin + rowo) + lane;
; #pragma unroll
;                             for (int j = 0; j < 4; ++j) v[q][j] = xr[64 * j]; }
;     ...
;                 for (int q = 0; q < 4; ++q) {
;                     const int i = wave + 8 * q;
;                     if (i < nrow && (q < 2 || k == 0)) {
;                         const int row = rbase + i;
;                         LAS f32x4* hrow = (LAS f32x4*)(hs + (row & 31) * 1024) + lane;
;                         float s = 0.f;
; #pragma unroll
;                         for (int j = 0; j < 4; ++j) s += (v[q][j][0] * v[q][j][0] + v[q][j][1] * v[q][j][1]) + (v[q][j][2] * v[q][j][2] + v[q][j][3] * v[q][j][3]);
;                         float rstd = rsqrtf(wave_sum(s) * (1.f / D) + EPS);
;                         if (ts0 == 0 && k == 0 && i < 15) rstd = 0.f;
; #pragma unroll
;                         for (int j = 0; j < 4; ++j) { const f32x4 gg = *((const f32x4*)g + lane + 64 * j); hrow[64 * j] = v[q][j] * rstd * gg; }
;                     }
.LBB0_88:
	s_waitcnt vmcnt(0)
	v_pk_mul_f32 v[34:35], v[32:33], v[32:33]
	v_pk_mul_f32 v[36:37], v[30:31], v[30:31]
	v_xor_b32_e32 v42, 1, v67
	v_pk_mov_b32 v[38:39], v[36:37], v[34:35] op_sel:[1,0]
	v_mov_b32_e32 v37, v35
	v_pk_add_f32 v[34:35], v[38:39], v[36:37]
	v_pk_mul_f32 v[36:37], v[28:29], v[28:29]
	v_pk_add_f32 v[34:35], v[34:35], v[34:35] op_sel_hi:[0,1]
	v_pk_mul_f32 v[38:39], v[26:27], v[26:27]
	v_mul_f32_e32 v34, v22, v22
	v_pk_mov_b32 v[40:41], v[38:39], v[36:37] op_sel:[1,0]
	v_mov_b32_e32 v39, v37
	v_pk_add_f32 v[36:37], v[40:41], v[38:39]
	v_pk_fma_f32 v[38:39], v[22:23], v[22:23], v[34:35] op_sel_hi:[1,1,0]
	v_mul_f32_e32 v34, v24, v24
	v_pk_add_f32 v[36:37], v[36:37], v[36:37] op_sel_hi:[0,1]
	v_pk_fma_f32 v[40:41], v[24:25], v[24:25], v[34:35] op_sel_hi:[1,1,0]
	v_mul_f32_e32 v38, v18, v18
	v_mul_f32_e32 v40, v19, v19
	v_mul_f32_e32 v36, v20, v20
	v_mul_f32_e32 v34, v21, v21
	v_pk_add_f32 v[38:39], v[38:39], v[40:41]
	v_pk_add_f32 v[34:35], v[36:37], v[34:35]
	v_xor_b32_e32 v52, 2, v67
	v_pk_add_f32 v[38:39], v[38:39], v[34:35]
	global_load_dwordx4 v[34:37], v[70:71], off nt
	v_add_f32_e32 v46, v38, v39
	v_and_b32_e32 v38, 64, v67
	v_add_u32_e32 v50, 64, v38
	v_cmp_lt_i32_e32 vcc, v42, v50
	global_load_dwordx4 v[38:41], v[70:71], off offset:1024 nt
	s_and_b64 s[18:19], s[12:13], s[30:31]
	v_cndmask_b32_e32 v42, v67, v42, vcc
	v_lshlrev_b32_e32 v42, 2, v42
	ds_bpermute_b32 v47, v42, v46
	global_load_dwordx4 v[42:45], v[70:71], off offset:2048 nt
	v_cmp_lt_i32_e32 vcc, v52, v50
	s_waitcnt lgkmcnt(0)
	v_add_f32_e32 v51, v46, v47
	global_load_dwordx4 v[46:49], v[70:71], off offset:3072 nt
	v_cndmask_b32_e32 v52, v67, v52, vcc
	v_lshlrev_b32_e32 v52, 2, v52
	ds_bpermute_b32 v52, v52, v51
	s_waitcnt lgkmcnt(0)
	v_add_f32_e32 v51, v51, v52
	v_xor_b32_e32 v52, 4, v67
	v_cmp_lt_i32_e32 vcc, v52, v50
	s_nop 1
	v_cndmask_b32_e32 v52, v67, v52, vcc
	v_lshlrev_b32_e32 v52, 2, v52
	ds_bpermute_b32 v52, v52, v51
	s_waitcnt lgkmcnt(0)
	v_add_f32_e32 v51, v51, v52
	v_xor_b32_e32 v52, 8, v67
	v_cmp_lt_i32_e32 vcc, v52, v50
	s_nop 1
	v_cndmask_b32_e32 v52, v67, v52, vcc
	v_lshlrev_b32_e32 v52, 2, v52
	ds_bpermute_b32 v52, v52, v51
	s_waitcnt lgkmcnt(0)
	v_add_f32_e32 v51, v51, v52
	v_xor_b32_e32 v52, 16, v67
	v_cmp_lt_i32_e32 vcc, v52, v50
	s_nop 1
	v_cndmask_b32_e32 v52, v67, v52, vcc
	v_lshlrev_b32_e32 v52, 2, v52
	ds_bpermute_b32 v52, v52, v51
	s_waitcnt lgkmcnt(0)
	v_add_f32_e32 v51, v51, v52
	v_xor_b32_e32 v52, 32, v67
	v_cmp_lt_i32_e32 vcc, v52, v50
	s_nop 1
	v_cndmask_b32_e32 v50, v67, v52, vcc
	v_lshlrev_b32_e32 v50, 2, v50
	ds_bpermute_b32 v50, v50, v51
	s_waitcnt lgkmcnt(0)
	v_add_f32_e32 v50, v51, v50
	v_fmamk_f32 v50, v50, 0x3a800000, v85
	v_mul_f32_e32 v51, 0x4b800000, v50
	v_cmp_gt_f32_e32 vcc, s45, v50
	s_nop 1
	v_cndmask_b32_e32 v50, v50, v51, vcc
	v_rsq_f32_e32 v50, v50
	v_add_lshl_u32 v51, s53, v81, 12
	v_and_b32_e32 v51, 0x1f000, v51
	v_add_u32_e32 v51, v77, v51
	v_mul_f32_e32 v52, 0x45800000, v50
	v_cndmask_b32_e32 v50, v50, v52, vcc
	v_cndmask_b32_e64 v50, v50, 0, s[18:19]
	v_pk_mul_f32 v[52:53], v[30:31], v[50:51] op_sel_hi:[1,0]
	v_pk_mul_f32 v[54:55], v[32:33], v[50:51] op_sel_hi:[1,0]
	s_waitcnt vmcnt(3)
	v_pk_mul_f32 v[34:35], v[34:35], v[52:53]
	v_pk_mul_f32 v[36:37], v[36:37], v[54:55]
	ds_write_b128 v51, v[34:37]
	v_pk_mul_f32 v[34:35], v[26:27], v[50:51] op_sel_hi:[1,0]
	v_pk_mul_f32 v[36:37], v[28:29], v[50:51] op_sel_hi:[1,0]
	s_waitcnt vmcnt(2)
	v_pk_mul_f32 v[34:35], v[38:39], v[34:35]
	v_pk_mul_f32 v[36:37], v[40:41], v[36:37]
	ds_write_b128 v51, v[34:37] offset:1024
	v_pk_mul_f32 v[34:35], v[22:23], v[50:51] op_sel_hi:[1,0]
	v_pk_mul_f32 v[36:37], v[24:25], v[50:51] op_sel_hi:[1,0]
	s_waitcnt vmcnt(1)
	v_pk_mul_f32 v[34:35], v[42:43], v[34:35]
	v_pk_mul_f32 v[36:37], v[44:45], v[36:37]
	ds_write_b128 v51, v[34:37] offset:2048
	v_pk_mul_f32 v[34:35], v[18:19], v[50:51] op_sel_hi:[1,0]
	v_pk_mul_f32 v[36:37], v[20:21], v[50:51] op_sel_hi:[1,0]
	s_waitcnt vmcnt(0)
	v_pk_mul_f32 v[34:35], v[46:47], v[34:35]
	v_pk_mul_f32 v[36:37], v[48:49], v[36:37]
	ds_write_b128 v51, v[34:37] offset:3072
	s_or_b64 exec, exec, s[0:1]
	s_and_b64 s[16:17], s[34:35], s[16:17]
	s_and_saveexec_b64 s[0:1], s[16:17]
	s_cbranch_execnz .LBB0_96
	s_branch .LBB0_97
.LBB0_89:
	v_ashrrev_i32_e32 v75, 31, v74
	v_lshlrev_b64 v[18:19], 12, v[74:75]
	v_lshl_add_u64 v[18:19], v[68:69], 0, v[18:19]
	global_load_dwordx4 v[30:33], v[18:19], off nt
	global_load_dwordx4 v[26:29], v[18:19], off offset:1024 nt
	global_load_dwordx4 v[22:25], v[18:19], off offset:2048 nt
	s_nop 0
	global_load_dwordx4 v[18:21], v[18:19], off offset:3072 nt
	v_cmp_le_i32_e64 s[38:39], s40, v82
	v_cmp_gt_i32_e64 s[16:17], s40, v82
	s_and_saveexec_b64 s[40:41], s[16:17]
	s_cbranch_execnz .LBB0_83

; __device__ __forceinline__ float bf_lo(unsigned w) { return __uint_as_float(w << 16); }
; __device__ __forceinline__ float bf_hi(unsigned w) { return __uint_as_float(w & 0xffff0000u); }
; template <bool IN_BF16> __device__ __forceinline__ void pool_prep(const void* xin_, const float* g, bf16_t* Y, LAS unsigned char* lds, int vcu, int G) {
;     ...
;                 for (int q = 0; q < 4; ++q) {
;                     const int i = wave + 8 * q; const bool ok = (i < nrow) && (((rbase + i) & (SEQ - 1)) <= ts0 + 15) ;
;                     const size_t rowo = (size_t)((i < nrow && rbase + i >= 0 && !(ts0 == 0 && k == 0 && i < 15)) ? rbase + i : T0) * D;
;                     if (q < 2 || k == 0) {
;                         if (IN_BF16) { const u32x2* xr = (const u32x2*)(xinb + rowo) + lane;
; #pragma unroll
;                             for (int j = 0; j < 4; ++j) { const u32x2 wv = xr[64 * j]; v[q][j] = (f32x4){bf_lo(wv.x), bf_hi(wv.x), bf_lo(wv.y), bf_hi(wv.y)}; } }
;                         else { const f32x4* xr = (const f32x4*)(xin + rowo) + lane;
; #pragma unroll
;                             for (int j = 0; j < 4; ++j) v[q][j] = xr[64 * j]; }
.LBB0_92:
	v_ashrrev_i32_e32 v75, 31, v74
	v_lshlrev_b64 v[2:3], 12, v[74:75]
	v_lshl_add_u64 v[2:3], v[68:69], 0, v[2:3]
	global_load_dwordx4 v[14:17], v[2:3], off nt
	global_load_dwordx4 v[10:13], v[2:3], off offset:1024 nt
	global_load_dwordx4 v[6:9], v[2:3], off offset:2048 nt
	s_nop 0
	global_load_dwordx4 v[2:5], v[2:3], off offset:3072 nt
	v_mbcnt_hi_u32_b32 v67, -1, v76
	s_and_saveexec_b64 s[0:1], s[22:23]
	s_cbranch_execnz .LBB0_86

; #define LAS __attribute__((address_space(3)))
; template <bool IN_BF16> __device__ __forceinline__ void pool_prep(const void* xin_, const float* g, bf16_t* Y, LAS unsigned char* lds, int vcu, int G) {
;     ...
;                 for (int q = 0; q < 4; ++q) {
;                     const int i = wave + 8 * q;
;                     if (i < nrow && (q < 2 || k == 0)) {
;                         const int row = rbase + i;
;                         LAS f32x4* hrow = (LAS f32x4*)(hs + (row & 31) * 1024) + lane;
;                         float s = 0.f;
; #pragma unroll
;                         for (int j = 0; j < 4; ++j) s += (v[q][j][0] * v[q][j][0] + v[q][j][1] * v[q][j][1]) + (v[q][j][2] * v[q][j][2] + v[q][j][3] * v[q][j][3]);
;                         float rstd = rsqrtf(wave_sum(s) * (1.f / D) + EPS);
;                         if (ts0 == 0 && k == 0 && i < 15) rstd = 0.f;
; #pragma unroll
;                         for (int j = 0; j < 4; ++j) { const f32x4 gg = *((const f32x4*)g + lane + 64 * j); hrow[64 * j] = v[q][j] * rstd * gg; }
;                     }
.LBB0_94:
	s_waitcnt vmcnt(3)
	v_pk_mul_f32 v[50:51], v[48:49], v[48:49]
	v_pk_mul_f32 v[52:53], v[46:47], v[46:47]
	v_xor_b32_e32 v58, 1, v67
	v_pk_mov_b32 v[54:55], v[52:53], v[50:51] op_sel:[1,0]
	v_mov_b32_e32 v53, v51
	v_pk_add_f32 v[50:51], v[54:55], v[52:53]
	s_waitcnt vmcnt(2)
	v_pk_mul_f32 v[52:53], v[44:45], v[44:45]
	v_pk_mul_f32 v[54:55], v[42:43], v[42:43]
	v_pk_add_f32 v[50:51], v[50:51], v[50:51] op_sel:[0,1] op_sel_hi:[1,0]
	v_pk_mov_b32 v[56:57], v[54:55], v[52:53] op_sel:[1,0]
	v_mov_b32_e32 v55, v53
	v_pk_add_f32 v[52:53], v[56:57], v[54:55]
	s_waitcnt vmcnt(0)
	v_mul_f32_e32 v54, v34, v34
	v_mul_f32_e32 v55, v35, v35
	v_pk_add_f32 v[52:53], v[52:53], v[52:53] op_sel:[0,1] op_sel_hi:[1,0]
	v_mov_b32_e32 v51, v54
	v_mov_b32_e32 v53, v55
	v_pk_add_f32 v[50:51], v[50:51], v[52:53]
	v_mul_f32_e32 v52, v39, v39
	v_mul_f32_e32 v54, v41, v41
	v_mul_f32_e32 v56, v36, v36
	v_mul_f32_e32 v57, v37, v37
	v_pk_fma_f32 v[52:53], v[38:39], v[38:39], v[52:53] op_sel_hi:[1,1,0]
	v_pk_fma_f32 v[54:55], v[40:41], v[40:41], v[54:55] op_sel_hi:[1,1,0]
	v_mov_b32_e32 v53, v56
	v_mov_b32_e32 v55, v57
	v_pk_add_f32 v[52:53], v[52:53], v[54:55]
	v_xor_b32_e32 v87, 2, v67
	v_pk_add_f32 v[54:55], v[50:51], v[52:53]
	global_load_dwordx4 v[50:53], v[70:71], off nt
	v_add_f32_e32 v62, v54, v55
	v_and_b32_e32 v54, 64, v67
	v_add_u32_e32 v74, 64, v54
	v_cmp_lt_i32_e32 vcc, v58, v74
	global_load_dwordx4 v[54:57], v[70:71], off offset:1024 nt
	s_and_b64 s[20:21], s[10:11], s[30:31]
	v_cndmask_b32_e32 v58, v67, v58, vcc
	v_lshlrev_b32_e32 v58, 2, v58
	ds_bpermute_b32 v63, v58, v62
	global_load_dwordx4 v[58:61], v[70:71], off offset:2048 nt
	v_cmp_lt_i32_e32 vcc, v87, v74
	s_waitcnt lgkmcnt(0)
	v_add_f32_e32 v75, v62, v63
	global_load_dwordx4 v[62:65], v[70:71], off offset:3072 nt
	v_cndmask_b32_e32 v87, v67, v87, vcc
	v_lshlrev_b32_e32 v87, 2, v87
	ds_bpermute_b32 v87, v87, v75
	s_waitcnt lgkmcnt(0)
	v_add_f32_e32 v75, v75, v87
	v_xor_b32_e32 v87, 4, v67
	v_cmp_lt_i32_e32 vcc, v87, v74
	s_nop 1
	v_cndmask_b32_e32 v87, v67, v87, vcc
	v_lshlrev_b32_e32 v87, 2, v87
	ds_bpermute_b32 v87, v87, v75
	s_waitcnt lgkmcnt(0)
	v_add_f32_e32 v75, v75, v87
	v_xor_b32_e32 v87, 8, v67
	v_cmp_lt_i32_e32 vcc, v87, v74
	s_nop 1
	v_cndmask_b32_e32 v87, v67, v87, vcc
	v_lshlrev_b32_e32 v87, 2, v87
	ds_bpermute_b32 v87, v87, v75
	s_waitcnt lgkmcnt(0)
	v_add_f32_e32 v75, v75, v87
	v_xor_b32_e32 v87, 16, v67
	v_cmp_lt_i32_e32 vcc, v87, v74
	s_nop 1
	v_cndmask_b32_e32 v87, v67, v87, vcc
	v_lshlrev_b32_e32 v87, 2, v87
	ds_bpermute_b32 v87, v87, v75
	s_waitcnt lgkmcnt(0)
	v_add_f32_e32 v75, v75, v87
	v_xor_b32_e32 v87, 32, v67
	v_cmp_lt_i32_e32 vcc, v87, v74
	s_nop 1
	v_cndmask_b32_e32 v74, v67, v87, vcc
	v_lshlrev_b32_e32 v74, 2, v74
	ds_bpermute_b32 v74, v74, v75
	s_waitcnt lgkmcnt(0)
	v_add_f32_e32 v74, v75, v74
	v_fmamk_f32 v74, v74, 0x3a800000, v85
	v_mul_f32_e32 v75, 0x4b800000, v74
	v_cmp_gt_f32_e32 vcc, s45, v74
	s_nop 1
	v_cndmask_b32_e32 v74, v74, v75, vcc
	v_rsq_f32_e32 v74, v74
	v_add_lshl_u32 v75, s54, v80, 12
	v_and_b32_e32 v75, 0x1f000, v75
	v_add_u32_e32 v75, v77, v75
	v_mul_f32_e32 v87, 0x45800000, v74
	v_cndmask_b32_e32 v74, v74, v87, vcc
	v_cndmask_b32_e64 v74, v74, 0, s[20:21]
	v_pk_mul_f32 v[46:47], v[46:47], v[74:75] op_sel_hi:[1,0]
	v_pk_mul_f32 v[48:49], v[48:49], v[74:75] op_sel_hi:[1,0]
	v_pk_mul_f32 v[42:43], v[42:43], v[74:75] op_sel_hi:[1,0]
	v_pk_mul_f32 v[44:45], v[44:45], v[74:75] op_sel_hi:[1,0]
	v_pk_mul_f32 v[38:39], v[38:39], v[74:75] op_sel_hi:[1,0]
	v_pk_mul_f32 v[40:41], v[40:41], v[74:75] op_sel_hi:[1,0]
	v_pk_mul_f32 v[34:35], v[34:35], v[74:75] op_sel_hi:[1,0]
	v_pk_mul_f32 v[36:37], v[36:37], v[74:75] op_sel_hi:[1,0]
	s_waitcnt vmcnt(3)
	v_pk_mul_f32 v[48:49], v[52:53], v[48:49]
	v_pk_mul_f32 v[46:47], v[50:51], v[46:47]
	s_waitcnt vmcnt(2)
	v_pk_mul_f32 v[44:45], v[56:57], v[44:45]
	v_pk_mul_f32 v[42:43], v[54:55], v[42:43]
	s_waitcnt vmcnt(1)
	v_pk_mul_f32 v[40:41], v[60:61], v[40:41]
	v_pk_mul_f32 v[38:39], v[58:59], v[38:39]
	s_waitcnt vmcnt(0)
	v_pk_mul_f32 v[36:37], v[64:65], v[36:37]
	v_pk_mul_f32 v[34:35], v[62:63], v[34:35]
	ds_write_b128 v75, v[46:49]
	ds_write_b128 v75, v[42:45] offset:1024
	ds_write_b128 v75, v[38:41] offset:2048
	ds_write_b128 v75, v[34:37] offset:3072
	s_or_b64 exec, exec, s[0:1]
	s_and_b64 s[18:19], s[34:35], s[18:19]
	s_and_saveexec_b64 s[0:1], s[18:19]
	s_cbranch_execnz .LBB0_88

; #define LAS __attribute__((address_space(3)))
; template <bool IN_BF16> __device__ __forceinline__ void pool_prep(const void* xin_, const float* g, bf16_t* Y, LAS unsigned char* lds, int vcu, int G) {
;     ...
;                 for (int q = 0; q < 4; ++q) {
;                     const int i = wave + 8 * q;
;                     if (i < nrow && (q < 2 || k == 0)) {
;                         const int row = rbase + i;
;                         LAS f32x4* hrow = (LAS f32x4*)(hs + (row & 31) * 1024) + lane;
;                         float s = 0.f;
; #pragma unroll
;                         for (int j = 0; j < 4; ++j) s += (v[q][j][0] * v[q][j][0] + v[q][j][1] * v[q][j][1]) + (v[q][j][2] * v[q][j][2] + v[q][j][3] * v[q][j][3]);
;                         float rstd = rsqrtf(wave_sum(s) * (1.f / D) + EPS);
;                         if (ts0 == 0 && k == 0 && i < 15) rstd = 0.f;
; #pragma unroll
;                         for (int j = 0; j < 4; ++j) { const f32x4 gg = *((const f32x4*)g + lane + 64 * j); hrow[64 * j] = v[q][j] * rstd * gg; }
;                     }
.LBB0_96:
	s_waitcnt vmcnt(0)
	v_pk_mul_f32 v[34:35], v[16:17], v[16:17]
	v_pk_mul_f32 v[36:37], v[14:15], v[14:15]
	v_xor_b32_e32 v42, 1, v67
	v_pk_mov_b32 v[38:39], v[36:37], v[34:35] op_sel:[1,0]
	v_mov_b32_e32 v37, v35
	v_pk_add_f32 v[34:35], v[38:39], v[36:37]
	v_pk_mul_f32 v[36:37], v[12:13], v[12:13]
	v_pk_add_f32 v[34:35], v[34:35], v[34:35] op_sel_hi:[0,1]
	v_pk_mul_f32 v[38:39], v[10:11], v[10:11]
	v_mul_f32_e32 v34, v6, v6
	v_pk_mov_b32 v[40:41], v[38:39], v[36:37] op_sel:[1,0]
	v_mov_b32_e32 v39, v37
	v_pk_add_f32 v[36:37], v[40:41], v[38:39]
	v_pk_fma_f32 v[38:39], v[6:7], v[6:7], v[34:35] op_sel_hi:[1,1,0]
	v_mul_f32_e32 v34, v8, v8
	v_pk_add_f32 v[36:37], v[36:37], v[36:37] op_sel_hi:[0,1]
	v_pk_fma_f32 v[40:41], v[8:9], v[8:9], v[34:35] op_sel_hi:[1,1,0]
	v_mul_f32_e32 v38, v2, v2
	v_mul_f32_e32 v40, v3, v3
	v_mul_f32_e32 v36, v4, v4
	v_mul_f32_e32 v34, v5, v5
	v_pk_add_f32 v[38:39], v[38:39], v[40:41]
	v_pk_add_f32 v[34:35], v[36:37], v[34:35]
	v_xor_b32_e32 v52, 2, v67
	v_pk_add_f32 v[38:39], v[38:39], v[34:35]
	global_load_dwordx4 v[34:37], v[70:71], off nt
	v_add_f32_e32 v46, v38, v39
	v_and_b32_e32 v38, 64, v67
	v_add_u32_e32 v50, 64, v38
	v_cmp_lt_i32_e32 vcc, v42, v50
	global_load_dwordx4 v[38:41], v[70:71], off offset:1024 nt
	s_and_b64 s[16:17], s[14:15], s[30:31]
	v_cndmask_b32_e32 v42, v67, v42, vcc
	v_lshlrev_b32_e32 v42, 2, v42
	ds_bpermute_b32 v47, v42, v46
	global_load_dwordx4 v[42:45], v[70:71], off offset:2048 nt
	v_cmp_lt_i32_e32 vcc, v52, v50
	s_waitcnt lgkmcnt(0)
	v_add_f32_e32 v51, v46, v47
	global_load_dwordx4 v[46:49], v[70:71], off offset:3072 nt
	v_cndmask_b32_e32 v52, v67, v52, vcc
	v_lshlrev_b32_e32 v52, 2, v52
	ds_bpermute_b32 v52, v52, v51
	s_waitcnt lgkmcnt(0)
	v_add_f32_e32 v51, v51, v52
	v_xor_b32_e32 v52, 4, v67
	v_cmp_lt_i32_e32 vcc, v52, v50
	s_nop 1
	v_cndmask_b32_e32 v52, v67, v52, vcc
	v_lshlrev_b32_e32 v52, 2, v52
	ds_bpermute_b32 v52, v52, v51
	s_waitcnt lgkmcnt(0)
	v_add_f32_e32 v51, v51, v52
	v_xor_b32_e32 v52, 8, v67
	v_cmp_lt_i32_e32 vcc, v52, v50
	s_nop 1
	v_cndmask_b32_e32 v52, v67, v52, vcc
	v_lshlrev_b32_e32 v52, 2, v52
	ds_bpermute_b32 v52, v52, v51
	s_waitcnt lgkmcnt(0)
	v_add_f32_e32 v51, v51, v52
	v_xor_b32_e32 v52, 16, v67
	v_cmp_lt_i32_e32 vcc, v52, v50
	s_nop 1
	v_cndmask_b32_e32 v52, v67, v52, vcc
	v_lshlrev_b32_e32 v52, 2, v52
	ds_bpermute_b32 v52, v52, v51
	s_waitcnt lgkmcnt(0)
	v_add_f32_e32 v51, v51, v52
	v_xor_b32_e32 v52, 32, v67
	v_cmp_lt_i32_e32 vcc, v52, v50
	s_nop 1
	v_cndmask_b32_e32 v50, v67, v52, vcc
	v_lshlrev_b32_e32 v50, 2, v50
	ds_bpermute_b32 v50, v50, v51
	s_waitcnt lgkmcnt(0)
	v_add_f32_e32 v50, v51, v50
	v_fmamk_f32 v50, v50, 0x3a800000, v85
	v_mul_f32_e32 v51, 0x4b800000, v50
	v_cmp_gt_f32_e32 vcc, s45, v50
	s_nop 1
	v_cndmask_b32_e32 v50, v50, v51, vcc
	v_rsq_f32_e32 v50, v50
	v_add_lshl_u32 v51, s53, v82, 12
	v_and_b32_e32 v51, 0x1f000, v51
	v_add_u32_e32 v51, v77, v51
	v_mul_f32_e32 v52, 0x45800000, v50
	v_cndmask_b32_e32 v50, v50, v52, vcc
	v_cndmask_b32_e64 v50, v50, 0, s[16:17]
	v_pk_mul_f32 v[52:53], v[14:15], v[50:51] op_sel_hi:[1,0]
	v_pk_mul_f32 v[54:55], v[16:17], v[50:51] op_sel_hi:[1,0]
	s_waitcnt vmcnt(3)
	v_pk_mul_f32 v[34:35], v[34:35], v[52:53]
	v_pk_mul_f32 v[36:37], v[36:37], v[54:55]
	ds_write_b128 v51, v[34:37]
	v_pk_mul_f32 v[34:35], v[10:11], v[50:51] op_sel_hi:[1,0]
	v_pk_mul_f32 v[36:37], v[12:13], v[50:51] op_sel_hi:[1,0]
	s_waitcnt vmcnt(2)
	v_pk_mul_f32 v[34:35], v[38:39], v[34:35]
	v_pk_mul_f32 v[36:37], v[40:41], v[36:37]
	ds_write_b128 v51, v[34:37] offset:1024
	v_pk_mul_f32 v[34:35], v[6:7], v[50:51] op_sel_hi:[1,0]
	v_pk_mul_f32 v[36:37], v[8:9], v[50:51] op_sel_hi:[1,0]
	s_waitcnt vmcnt(1)
	v_pk_mul_f32 v[34:35], v[42:43], v[34:35]
	v_pk_mul_f32 v[36:37], v[44:45], v[36:37]
	ds_write_b128 v51, v[34:37] offset:2048
	v_pk_mul_f32 v[34:35], v[2:3], v[50:51] op_sel_hi:[1,0]
	v_pk_mul_f32 v[36:37], v[4:5], v[50:51] op_sel_hi:[1,0]
	s_waitcnt vmcnt(0)
	v_pk_mul_f32 v[34:35], v[46:47], v[34:35]
	v_pk_mul_f32 v[36:37], v[48:49], v[36:37]
	ds_write_b128 v51, v[34:37] offset:3072
